# plus: gmlp LN transpose via ds_write_b128 (was 32-way conflicted b16 writes), batched sel loads in ctx_mini_gemm merge and MergeHook (were serialized load-wait chains), hyena data-load conditional loa
# speedup vs baseline: 1.0370x; 1.0370x over previous
; __device__ __forceinline__ float bf2f(unsigned b) { return __uint_as_float(b << 16); }
;     __device__ __forceinline__ void operator()(f32x4 (&acc)[2][2][4][2], const pg8::Unit& u, int wr, int wc, int fr, int fq, int t) const {
;     ...
;         const int i = t >> 3;
;         const int row0 = u.pm * 256 + wr * 64 + fr, col0 = u.pn * 256 + wc * 32 + 4 * fq;
; #pragma unroll
;         for (int ai = 0; ai < 2; ++ai)
; #pragma unroll
;             for (int m = 0; m < 4; ++m) { const bf16* sp = sel + (size_t)(row0 + ai * 128 + m * 16) * 3072 + (i - 1) * 1024 + col0;
; #pragma unroll
;                 for (int bj = 0; bj < 2; ++bj)
; #pragma unroll
;                     for (int n = 0; n < 2; ++n) { const u32x2 a = *(const u32x2*)(sp + bj * 128 + n * 16), b = *(const u32x2*)(sp + 1024 + bj * 128 + n * 16);
;                         f32x4 r; r[0] = bf2f(a.x & 0xffffu) * __builtin_amdgcn_rcpf(fmaxf(bf2f(b.x & 0xffffu), 1e-30f)); r[1] = bf2f(a.x >> 16) * __builtin_amdgcn_rcpf(fmaxf(bf2f(b.x >> 16), 1e-30f));
;                         r[2] = bf2f(a.y & 0xffffu) * __builtin_amdgcn_rcpf(fmaxf(bf2f(b.y & 0xffffu), 1e-30f)); r[3] = bf2f(a.y >> 16) * __builtin_amdgcn_rcpf(fmaxf(bf2f(b.y >> 16), 1e-30f));
;                         acc[ai][bj][m][n] = acc[ai][bj][m][n] * r; }
;                 asm volatile("" ::: "memory"); }
.LBB0_125:
	v_mov_b32_e32 v96, v154
	v_mov_b32_e32 v98, v155
	v_readlane_b32 s4, v251, 28
	v_readlane_b32 s5, v251, 29
	v_lshl_add_u32 v138, v98, 2, s84
	v_add_u32_e32 v96, s93, v96
	s_and_b32 s39, s54, 0xc00
	v_mov_b64_e32 v[98:99], s[4:5]
	s_add_i32 s48, s39, 0xfffffc00
	s_mov_b32 s49, s92
	v_mad_i64_i32 v[140:141], s[58:59], v96, s78, v[98:99]
	v_ashrrev_i32_e32 v139, 31, v138
	s_lshl_b64 s[58:59], s[48:49], 1
	v_lshl_add_u64 v[140:141], v[140:141], 0, s[58:59]
	v_lshlrev_b64 v[148:149], 1, v[138:139]
	v_lshl_add_u64 v[150:151], v[140:141], 0, v[148:149]
	global_load_dwordx2 v[160:161], v[150:151], off
	global_load_dwordx2 v[162:163], v[150:151], off offset:2048
	global_load_dwordx2 v[164:165], v[150:151], off offset:32
	global_load_dwordx2 v[166:167], v[150:151], off offset:2080
	global_load_dwordx2 v[168:169], v[150:151], off offset:256
	global_load_dwordx2 v[170:171], v[150:151], off offset:2304
	global_load_dwordx2 v[172:173], v[150:151], off offset:288
	global_load_dwordx2 v[174:175], v[150:151], off offset:2336
	v_add_u32_e32 v150, 16, v96
	v_mad_i64_i32 v[150:151], s[48:49], v150, s78, v[98:99]
	v_lshl_add_u64 v[150:151], v[150:151], 0, s[58:59]
	v_lshl_add_u64 v[150:151], v[150:151], 0, v[148:149]
	global_load_dwordx2 v[176:177], v[150:151], off
	global_load_dwordx2 v[178:179], v[150:151], off offset:2048
	global_load_dwordx2 v[180:181], v[150:151], off offset:32
	global_load_dwordx2 v[182:183], v[150:151], off offset:2080
	global_load_dwordx2 v[184:185], v[150:151], off offset:256
	global_load_dwordx2 v[186:187], v[150:151], off offset:2304
	global_load_dwordx2 v[188:189], v[150:151], off offset:288
	global_load_dwordx2 v[190:191], v[150:151], off offset:2336
	v_add_u32_e32 v150, 32, v96
	v_mad_i64_i32 v[150:151], s[48:49], v150, s78, v[98:99]
	v_lshl_add_u64 v[150:151], v[150:151], 0, s[58:59]
	v_lshl_add_u64 v[150:151], v[150:151], 0, v[148:149]
	global_load_dwordx2 v[192:193], v[150:151], off
	global_load_dwordx2 v[194:195], v[150:151], off offset:2048
	global_load_dwordx2 v[196:197], v[150:151], off offset:32
	global_load_dwordx2 v[198:199], v[150:151], off offset:2080
	global_load_dwordx2 v[200:201], v[150:151], off offset:256
	global_load_dwordx2 v[202:203], v[150:151], off offset:2304
	global_load_dwordx2 v[204:205], v[150:151], off offset:288
	global_load_dwordx2 v[206:207], v[150:151], off offset:2336
	s_waitcnt vmcnt(22)
	v_lshlrev_b32_e32 v138, 16, v162
	v_and_b32_e32 v139, 0xffff0000, v162
	v_lshlrev_b32_e32 v140, 16, v163
	v_and_b32_e32 v141, 0xffff0000, v163
	v_max_f32_e32 v138, v138, v138
	v_max_f32_e32 v139, v139, v139
	v_max_f32_e32 v140, v140, v140
	v_max_f32_e32 v141, v141, v141
	v_max_f32_e32 v138, 0xda24260, v138
	v_max_f32_e32 v139, 0xda24260, v139
	v_max_f32_e32 v140, 0xda24260, v140
	v_max_f32_e32 v141, 0xda24260, v141
	v_rcp_f32_e32 v138, v138
	v_rcp_f32_e32 v139, v139
	v_rcp_f32_e32 v140, v140
	v_rcp_f32_e32 v141, v141
	v_lshlrev_b32_e32 v150, 16, v160
	v_and_b32_e32 v151, 0xffff0000, v160
	v_lshlrev_b32_e32 v152, 16, v161
	v_and_b32_e32 v153, 0xffff0000, v161
	v_pk_mul_f32 v[138:139], v[138:139], v[150:151]
	v_pk_mul_f32 v[140:141], v[140:141], v[152:153]
	v_pk_mul_f32 v[128:129], v[128:129], v[138:139]
	v_pk_mul_f32 v[130:131], v[130:131], v[140:141]
	s_waitcnt vmcnt(20)
	v_lshlrev_b32_e32 v138, 16, v166
	v_and_b32_e32 v139, 0xffff0000, v166
	v_lshlrev_b32_e32 v140, 16, v167
	v_and_b32_e32 v141, 0xffff0000, v167
	v_max_f32_e32 v138, v138, v138
	v_max_f32_e32 v139, v139, v139
	v_max_f32_e32 v140, v140, v140
	v_max_f32_e32 v141, v141, v141
	v_max_f32_e32 v138, 0xda24260, v138
	v_max_f32_e32 v139, 0xda24260, v139
	v_max_f32_e32 v140, 0xda24260, v140
	v_max_f32_e32 v141, 0xda24260, v141
	v_rcp_f32_e32 v138, v138
	v_rcp_f32_e32 v139, v139
	v_rcp_f32_e32 v140, v140
	v_rcp_f32_e32 v141, v141
	v_lshlrev_b32_e32 v150, 16, v164
	v_and_b32_e32 v151, 0xffff0000, v164
	v_lshlrev_b32_e32 v152, 16, v165
	v_and_b32_e32 v153, 0xffff0000, v165
	v_pk_mul_f32 v[138:139], v[138:139], v[150:151]
	v_pk_mul_f32 v[140:141], v[140:141], v[152:153]
	v_pk_mul_f32 v[124:125], v[124:125], v[138:139]
	v_pk_mul_f32 v[126:127], v[126:127], v[140:141]
	s_waitcnt vmcnt(18)
	v_lshlrev_b32_e32 v138, 16, v170
	v_and_b32_e32 v139, 0xffff0000, v170
	v_lshlrev_b32_e32 v140, 16, v171
	v_and_b32_e32 v141, 0xffff0000, v171
	v_max_f32_e32 v138, v138, v138
	v_max_f32_e32 v139, v139, v139
	v_max_f32_e32 v140, v140, v140
	v_max_f32_e32 v141, v141, v141
	v_max_f32_e32 v138, 0xda24260, v138
	v_max_f32_e32 v139, 0xda24260, v139
	v_max_f32_e32 v140, 0xda24260, v140
	v_max_f32_e32 v141, 0xda24260, v141
	v_rcp_f32_e32 v138, v138
	v_rcp_f32_e32 v139, v139
	v_rcp_f32_e32 v140, v140
	v_rcp_f32_e32 v141, v141
	v_lshlrev_b32_e32 v150, 16, v168
	v_and_b32_e32 v151, 0xffff0000, v168
	v_lshlrev_b32_e32 v152, 16, v169
	v_and_b32_e32 v153, 0xffff0000, v169
	v_pk_mul_f32 v[138:139], v[138:139], v[150:151]
	v_pk_mul_f32 v[140:141], v[140:141], v[152:153]
	v_pk_mul_f32 v[120:121], v[120:121], v[138:139]
	v_pk_mul_f32 v[122:123], v[122:123], v[140:141]
	s_waitcnt vmcnt(16)
	v_lshlrev_b32_e32 v138, 16, v174
	v_and_b32_e32 v139, 0xffff0000, v174
	v_lshlrev_b32_e32 v140, 16, v175
	v_and_b32_e32 v141, 0xffff0000, v175
	v_max_f32_e32 v138, v138, v138
	v_max_f32_e32 v139, v139, v139
	v_max_f32_e32 v140, v140, v140
	v_max_f32_e32 v141, v141, v141
	v_max_f32_e32 v138, 0xda24260, v138
	v_max_f32_e32 v139, 0xda24260, v139
	v_max_f32_e32 v140, 0xda24260, v140
	v_max_f32_e32 v141, 0xda24260, v141
	v_rcp_f32_e32 v138, v138
	v_rcp_f32_e32 v139, v139
	v_rcp_f32_e32 v140, v140
	v_rcp_f32_e32 v141, v141
	v_lshlrev_b32_e32 v150, 16, v172
	v_and_b32_e32 v151, 0xffff0000, v172
	v_lshlrev_b32_e32 v152, 16, v173
	v_and_b32_e32 v153, 0xffff0000, v173
	v_pk_mul_f32 v[138:139], v[138:139], v[150:151]
	v_pk_mul_f32 v[140:141], v[140:141], v[152:153]
	v_pk_mul_f32 v[116:117], v[116:117], v[138:139]
	v_pk_mul_f32 v[118:119], v[118:119], v[140:141]
	s_waitcnt vmcnt(14)
; __device__ __forceinline__ float bf2f(unsigned b) { return __uint_as_float(b << 16); }
;     __device__ __forceinline__ void operator()(f32x4 (&acc)[2][2][4][2], const pg8::Unit& u, int wr, int wc, int fr, int fq, int t) const {
;     ...
;         const int i = t >> 3;
;         const int row0 = u.pm * 256 + wr * 64 + fr, col0 = u.pn * 256 + wc * 32 + 4 * fq;
; #pragma unroll
;         for (int ai = 0; ai < 2; ++ai)
; #pragma unroll
;             for (int m = 0; m < 4; ++m) { const bf16* sp = sel + (size_t)(row0 + ai * 128 + m * 16) * 3072 + (i - 1) * 1024 + col0;
; #pragma unroll
;                 for (int bj = 0; bj < 2; ++bj)
; #pragma unroll
;                     for (int n = 0; n < 2; ++n) { const u32x2 a = *(const u32x2*)(sp + bj * 128 + n * 16), b = *(const u32x2*)(sp + 1024 + bj * 128 + n * 16);
;                         f32x4 r; r[0] = bf2f(a.x & 0xffffu) * __builtin_amdgcn_rcpf(fmaxf(bf2f(b.x & 0xffffu), 1e-30f)); r[1] = bf2f(a.x >> 16) * __builtin_amdgcn_rcpf(fmaxf(bf2f(b.x >> 16), 1e-30f));
;                         r[2] = bf2f(a.y & 0xffffu) * __builtin_amdgcn_rcpf(fmaxf(bf2f(b.y & 0xffffu), 1e-30f)); r[3] = bf2f(a.y >> 16) * __builtin_amdgcn_rcpf(fmaxf(bf2f(b.y >> 16), 1e-30f));
;                         acc[ai][bj][m][n] = acc[ai][bj][m][n] * r; }
;                 asm volatile("" ::: "memory"); }
	v_lshlrev_b32_e32 v138, 16, v178
	v_and_b32_e32 v139, 0xffff0000, v178
	v_lshlrev_b32_e32 v140, 16, v179
	v_and_b32_e32 v141, 0xffff0000, v179
	v_max_f32_e32 v138, v138, v138
	v_max_f32_e32 v139, v139, v139
	v_max_f32_e32 v140, v140, v140
	v_max_f32_e32 v141, v141, v141
	v_max_f32_e32 v138, 0xda24260, v138
	v_max_f32_e32 v139, 0xda24260, v139
	v_max_f32_e32 v140, 0xda24260, v140
	v_max_f32_e32 v141, 0xda24260, v141
	v_rcp_f32_e32 v138, v138
	v_rcp_f32_e32 v139, v139
	v_rcp_f32_e32 v140, v140
	v_rcp_f32_e32 v141, v141
	v_lshlrev_b32_e32 v150, 16, v176
	v_and_b32_e32 v151, 0xffff0000, v176
	v_lshlrev_b32_e32 v152, 16, v177
	v_and_b32_e32 v153, 0xffff0000, v177
	v_pk_mul_f32 v[138:139], v[138:139], v[150:151]
	v_pk_mul_f32 v[140:141], v[140:141], v[152:153]
	v_pk_mul_f32 v[112:113], v[112:113], v[138:139]
	v_pk_mul_f32 v[114:115], v[114:115], v[140:141]
	s_waitcnt vmcnt(12)
	v_lshlrev_b32_e32 v138, 16, v182
	v_and_b32_e32 v139, 0xffff0000, v182
	v_lshlrev_b32_e32 v140, 16, v183
	v_and_b32_e32 v141, 0xffff0000, v183
	v_max_f32_e32 v138, v138, v138
	v_max_f32_e32 v139, v139, v139
	v_max_f32_e32 v140, v140, v140
	v_max_f32_e32 v141, v141, v141
	v_max_f32_e32 v138, 0xda24260, v138
	v_max_f32_e32 v139, 0xda24260, v139
	v_max_f32_e32 v140, 0xda24260, v140
	v_max_f32_e32 v141, 0xda24260, v141
	v_rcp_f32_e32 v138, v138
	v_rcp_f32_e32 v139, v139
	v_rcp_f32_e32 v140, v140
	v_rcp_f32_e32 v141, v141
	v_lshlrev_b32_e32 v150, 16, v180
	v_and_b32_e32 v151, 0xffff0000, v180
	v_lshlrev_b32_e32 v152, 16, v181
	v_and_b32_e32 v153, 0xffff0000, v181
	v_pk_mul_f32 v[138:139], v[138:139], v[150:151]
	v_pk_mul_f32 v[140:141], v[140:141], v[152:153]
	v_pk_mul_f32 v[108:109], v[108:109], v[138:139]
	v_pk_mul_f32 v[110:111], v[110:111], v[140:141]
	s_waitcnt vmcnt(10)
	v_lshlrev_b32_e32 v138, 16, v186
	v_and_b32_e32 v139, 0xffff0000, v186
	v_lshlrev_b32_e32 v140, 16, v187
	v_and_b32_e32 v141, 0xffff0000, v187
	v_max_f32_e32 v138, v138, v138
	v_max_f32_e32 v139, v139, v139
	v_max_f32_e32 v140, v140, v140
	v_max_f32_e32 v141, v141, v141
	v_max_f32_e32 v138, 0xda24260, v138
	v_max_f32_e32 v139, 0xda24260, v139
	v_max_f32_e32 v140, 0xda24260, v140
	v_max_f32_e32 v141, 0xda24260, v141
	v_rcp_f32_e32 v138, v138
	v_rcp_f32_e32 v139, v139
	v_rcp_f32_e32 v140, v140
	v_rcp_f32_e32 v141, v141
	v_lshlrev_b32_e32 v150, 16, v184
	v_and_b32_e32 v151, 0xffff0000, v184
	v_lshlrev_b32_e32 v152, 16, v185
	v_and_b32_e32 v153, 0xffff0000, v185
	v_pk_mul_f32 v[138:139], v[138:139], v[150:151]
	v_pk_mul_f32 v[140:141], v[140:141], v[152:153]
	v_pk_mul_f32 v[104:105], v[104:105], v[138:139]
	v_pk_mul_f32 v[106:107], v[106:107], v[140:141]
	s_waitcnt vmcnt(8)
	v_lshlrev_b32_e32 v138, 16, v190
	v_and_b32_e32 v139, 0xffff0000, v190
	v_lshlrev_b32_e32 v140, 16, v191
	v_and_b32_e32 v141, 0xffff0000, v191
	v_max_f32_e32 v138, v138, v138
	v_max_f32_e32 v139, v139, v139
	v_max_f32_e32 v140, v140, v140
	v_max_f32_e32 v141, v141, v141
	v_max_f32_e32 v138, 0xda24260, v138
	v_max_f32_e32 v139, 0xda24260, v139
	v_max_f32_e32 v140, 0xda24260, v140
	v_max_f32_e32 v141, 0xda24260, v141
	v_rcp_f32_e32 v138, v138
	v_rcp_f32_e32 v139, v139
	v_rcp_f32_e32 v140, v140
	v_rcp_f32_e32 v141, v141
	v_lshlrev_b32_e32 v150, 16, v188
	v_and_b32_e32 v151, 0xffff0000, v188
	v_lshlrev_b32_e32 v152, 16, v189
	v_and_b32_e32 v153, 0xffff0000, v189
	v_pk_mul_f32 v[138:139], v[138:139], v[150:151]
	v_pk_mul_f32 v[140:141], v[140:141], v[152:153]
	v_pk_mul_f32 v[100:101], v[100:101], v[138:139]
	v_pk_mul_f32 v[102:103], v[102:103], v[140:141]
	s_waitcnt vmcnt(6)
	v_lshlrev_b32_e32 v138, 16, v194
	v_and_b32_e32 v139, 0xffff0000, v194
	v_lshlrev_b32_e32 v140, 16, v195
	v_and_b32_e32 v141, 0xffff0000, v195
	v_max_f32_e32 v138, v138, v138
	v_max_f32_e32 v139, v139, v139
	v_max_f32_e32 v140, v140, v140
	v_max_f32_e32 v141, v141, v141
	v_max_f32_e32 v138, 0xda24260, v138
	v_max_f32_e32 v139, 0xda24260, v139
	v_max_f32_e32 v140, 0xda24260, v140
	v_max_f32_e32 v141, 0xda24260, v141
	v_rcp_f32_e32 v138, v138
	v_rcp_f32_e32 v139, v139
	v_rcp_f32_e32 v140, v140
	v_rcp_f32_e32 v141, v141
	v_lshlrev_b32_e32 v150, 16, v192
	v_and_b32_e32 v151, 0xffff0000, v192
	v_lshlrev_b32_e32 v152, 16, v193
	v_and_b32_e32 v153, 0xffff0000, v193
	v_pk_mul_f32 v[138:139], v[138:139], v[150:151]
	v_pk_mul_f32 v[140:141], v[140:141], v[152:153]
	v_pk_mul_f32 v[92:93], v[92:93], v[138:139]
	v_pk_mul_f32 v[94:95], v[94:95], v[140:141]
	s_waitcnt vmcnt(4)
	v_lshlrev_b32_e32 v138, 16, v198
	v_and_b32_e32 v139, 0xffff0000, v198
	v_lshlrev_b32_e32 v140, 16, v199
	v_and_b32_e32 v141, 0xffff0000, v199
	v_max_f32_e32 v138, v138, v138
	v_max_f32_e32 v139, v139, v139
	v_max_f32_e32 v140, v140, v140
	v_max_f32_e32 v141, v141, v141
	v_max_f32_e32 v138, 0xda24260, v138
	v_max_f32_e32 v139, 0xda24260, v139
	v_max_f32_e32 v140, 0xda24260, v140
	v_max_f32_e32 v141, 0xda24260, v141
	v_rcp_f32_e32 v138, v138
	v_rcp_f32_e32 v139, v139
	v_rcp_f32_e32 v140, v140
	v_rcp_f32_e32 v141, v141
	v_lshlrev_b32_e32 v150, 16, v196
	v_and_b32_e32 v151, 0xffff0000, v196
	v_lshlrev_b32_e32 v152, 16, v197
	v_and_b32_e32 v153, 0xffff0000, v197
	v_pk_mul_f32 v[138:139], v[138:139], v[150:151]
	v_pk_mul_f32 v[140:141], v[140:141], v[152:153]
	v_pk_mul_f32 v[88:89], v[88:89], v[138:139]
	v_pk_mul_f32 v[90:91], v[90:91], v[140:141]
	s_waitcnt vmcnt(2)
; __device__ __forceinline__ float bf2f(unsigned b) { return __uint_as_float(b << 16); }
;     __device__ __forceinline__ void operator()(f32x4 (&acc)[2][2][4][2], const pg8::Unit& u, int wr, int wc, int fr, int fq, int t) const {
;     ...
;         const int i = t >> 3;
;         const int row0 = u.pm * 256 + wr * 64 + fr, col0 = u.pn * 256 + wc * 32 + 4 * fq;
; #pragma unroll
;         for (int ai = 0; ai < 2; ++ai)
; #pragma unroll
;             for (int m = 0; m < 4; ++m) { const bf16* sp = sel + (size_t)(row0 + ai * 128 + m * 16) * 3072 + (i - 1) * 1024 + col0;
; #pragma unroll
;                 for (int bj = 0; bj < 2; ++bj)
; #pragma unroll
;                     for (int n = 0; n < 2; ++n) { const u32x2 a = *(const u32x2*)(sp + bj * 128 + n * 16), b = *(const u32x2*)(sp + 1024 + bj * 128 + n * 16);
;                         f32x4 r; r[0] = bf2f(a.x & 0xffffu) * __builtin_amdgcn_rcpf(fmaxf(bf2f(b.x & 0xffffu), 1e-30f)); r[1] = bf2f(a.x >> 16) * __builtin_amdgcn_rcpf(fmaxf(bf2f(b.x >> 16), 1e-30f));
;                         r[2] = bf2f(a.y & 0xffffu) * __builtin_amdgcn_rcpf(fmaxf(bf2f(b.y & 0xffffu), 1e-30f)); r[3] = bf2f(a.y >> 16) * __builtin_amdgcn_rcpf(fmaxf(bf2f(b.y >> 16), 1e-30f));
;                         acc[ai][bj][m][n] = acc[ai][bj][m][n] * r; }
;                 asm volatile("" ::: "memory"); }
	v_lshlrev_b32_e32 v138, 16, v202
	v_and_b32_e32 v139, 0xffff0000, v202
	v_lshlrev_b32_e32 v140, 16, v203
	v_and_b32_e32 v141, 0xffff0000, v203
	v_max_f32_e32 v138, v138, v138
	v_max_f32_e32 v139, v139, v139
	v_max_f32_e32 v140, v140, v140
	v_max_f32_e32 v141, v141, v141
	v_max_f32_e32 v138, 0xda24260, v138
	v_max_f32_e32 v139, 0xda24260, v139
	v_max_f32_e32 v140, 0xda24260, v140
	v_max_f32_e32 v141, 0xda24260, v141
	v_rcp_f32_e32 v138, v138
	v_rcp_f32_e32 v139, v139
	v_rcp_f32_e32 v140, v140
	v_rcp_f32_e32 v141, v141
	v_lshlrev_b32_e32 v150, 16, v200
	v_and_b32_e32 v151, 0xffff0000, v200
	v_lshlrev_b32_e32 v152, 16, v201
	v_and_b32_e32 v153, 0xffff0000, v201
	v_pk_mul_f32 v[138:139], v[138:139], v[150:151]
	v_pk_mul_f32 v[140:141], v[140:141], v[152:153]
	v_pk_mul_f32 v[84:85], v[84:85], v[138:139]
	v_pk_mul_f32 v[86:87], v[86:87], v[140:141]
	s_waitcnt vmcnt(0)
	v_lshlrev_b32_e32 v138, 16, v206
	v_and_b32_e32 v139, 0xffff0000, v206
	v_lshlrev_b32_e32 v140, 16, v207
	v_and_b32_e32 v141, 0xffff0000, v207
	v_max_f32_e32 v138, v138, v138
	v_max_f32_e32 v139, v139, v139
	v_max_f32_e32 v140, v140, v140
	v_max_f32_e32 v141, v141, v141
	v_max_f32_e32 v138, 0xda24260, v138
	v_max_f32_e32 v139, 0xda24260, v139
	v_max_f32_e32 v140, 0xda24260, v140
	v_max_f32_e32 v141, 0xda24260, v141
	v_rcp_f32_e32 v138, v138
	v_rcp_f32_e32 v139, v139
	v_rcp_f32_e32 v140, v140
	v_rcp_f32_e32 v141, v141
	v_lshlrev_b32_e32 v150, 16, v204
	v_and_b32_e32 v151, 0xffff0000, v204
	v_lshlrev_b32_e32 v152, 16, v205
	v_and_b32_e32 v153, 0xffff0000, v205
	v_pk_mul_f32 v[138:139], v[138:139], v[150:151]
	v_pk_mul_f32 v[140:141], v[140:141], v[152:153]
	v_pk_mul_f32 v[80:81], v[80:81], v[138:139]
	v_pk_mul_f32 v[82:83], v[82:83], v[140:141]
	v_add_u32_e32 v150, 48, v96
	v_mad_i64_i32 v[150:151], s[48:49], v150, s78, v[98:99]
	v_lshl_add_u64 v[150:151], v[150:151], 0, s[58:59]
	v_lshl_add_u64 v[150:151], v[150:151], 0, v[148:149]
	global_load_dwordx2 v[160:161], v[150:151], off
	global_load_dwordx2 v[162:163], v[150:151], off offset:2048
	global_load_dwordx2 v[164:165], v[150:151], off offset:32
	global_load_dwordx2 v[166:167], v[150:151], off offset:2080
	global_load_dwordx2 v[168:169], v[150:151], off offset:256
	global_load_dwordx2 v[170:171], v[150:151], off offset:2304
	global_load_dwordx2 v[172:173], v[150:151], off offset:288
	global_load_dwordx2 v[174:175], v[150:151], off offset:2336
	v_add_u32_e32 v150, 128, v96
	v_mad_i64_i32 v[150:151], s[48:49], v150, s78, v[98:99]
	v_lshl_add_u64 v[150:151], v[150:151], 0, s[58:59]
	v_lshl_add_u64 v[150:151], v[150:151], 0, v[148:149]
	global_load_dwordx2 v[176:177], v[150:151], off
	global_load_dwordx2 v[178:179], v[150:151], off offset:2048
	global_load_dwordx2 v[180:181], v[150:151], off offset:32
	global_load_dwordx2 v[182:183], v[150:151], off offset:2080
	global_load_dwordx2 v[184:185], v[150:151], off offset:256
	global_load_dwordx2 v[186:187], v[150:151], off offset:2304
	global_load_dwordx2 v[188:189], v[150:151], off offset:288
	global_load_dwordx2 v[190:191], v[150:151], off offset:2336
	v_add_u32_e32 v150, 144, v96
	v_mad_i64_i32 v[150:151], s[48:49], v150, s78, v[98:99]
	v_lshl_add_u64 v[150:151], v[150:151], 0, s[58:59]
	v_lshl_add_u64 v[150:151], v[150:151], 0, v[148:149]
	global_load_dwordx2 v[192:193], v[150:151], off
	global_load_dwordx2 v[194:195], v[150:151], off offset:2048
	global_load_dwordx2 v[196:197], v[150:151], off offset:32
	global_load_dwordx2 v[198:199], v[150:151], off offset:2080
	global_load_dwordx2 v[200:201], v[150:151], off offset:256
	global_load_dwordx2 v[202:203], v[150:151], off offset:2304
	global_load_dwordx2 v[204:205], v[150:151], off offset:288
	global_load_dwordx2 v[206:207], v[150:151], off offset:2336
	s_waitcnt vmcnt(22)
	v_lshlrev_b32_e32 v138, 16, v162
	v_and_b32_e32 v139, 0xffff0000, v162
	v_lshlrev_b32_e32 v140, 16, v163
	v_and_b32_e32 v141, 0xffff0000, v163
	v_max_f32_e32 v138, v138, v138
	v_max_f32_e32 v139, v139, v139
	v_max_f32_e32 v140, v140, v140
	v_max_f32_e32 v141, v141, v141
	v_max_f32_e32 v138, 0xda24260, v138
	v_max_f32_e32 v139, 0xda24260, v139
	v_max_f32_e32 v140, 0xda24260, v140
	v_max_f32_e32 v141, 0xda24260, v141
	v_rcp_f32_e32 v138, v138
	v_rcp_f32_e32 v139, v139
	v_rcp_f32_e32 v140, v140
	v_rcp_f32_e32 v141, v141
	v_lshlrev_b32_e32 v150, 16, v160
	v_and_b32_e32 v151, 0xffff0000, v160
	v_lshlrev_b32_e32 v152, 16, v161
	v_and_b32_e32 v153, 0xffff0000, v161
	v_pk_mul_f32 v[138:139], v[138:139], v[150:151]
	v_pk_mul_f32 v[140:141], v[140:141], v[152:153]
	v_pk_mul_f32 v[76:77], v[76:77], v[138:139]
	v_pk_mul_f32 v[78:79], v[78:79], v[140:141]
	s_waitcnt vmcnt(20)
	v_lshlrev_b32_e32 v138, 16, v166
	v_and_b32_e32 v139, 0xffff0000, v166
	v_lshlrev_b32_e32 v140, 16, v167
	v_and_b32_e32 v141, 0xffff0000, v167
	v_max_f32_e32 v138, v138, v138
	v_max_f32_e32 v139, v139, v139
	v_max_f32_e32 v140, v140, v140
	v_max_f32_e32 v141, v141, v141
	v_max_f32_e32 v138, 0xda24260, v138
	v_max_f32_e32 v139, 0xda24260, v139
	v_max_f32_e32 v140, 0xda24260, v140
	v_max_f32_e32 v141, 0xda24260, v141
	v_rcp_f32_e32 v138, v138
	v_rcp_f32_e32 v139, v139
	v_rcp_f32_e32 v140, v140
	v_rcp_f32_e32 v141, v141
	v_lshlrev_b32_e32 v150, 16, v164
	v_and_b32_e32 v151, 0xffff0000, v164
	v_lshlrev_b32_e32 v152, 16, v165
	v_and_b32_e32 v153, 0xffff0000, v165
	v_pk_mul_f32 v[138:139], v[138:139], v[150:151]
	v_pk_mul_f32 v[140:141], v[140:141], v[152:153]
	v_pk_mul_f32 v[72:73], v[72:73], v[138:139]
	v_pk_mul_f32 v[74:75], v[74:75], v[140:141]
	s_waitcnt vmcnt(18)
; __device__ __forceinline__ float bf2f(unsigned b) { return __uint_as_float(b << 16); }
;     __device__ __forceinline__ void operator()(f32x4 (&acc)[2][2][4][2], const pg8::Unit& u, int wr, int wc, int fr, int fq, int t) const {
;     ...
;         const int i = t >> 3;
;         const int row0 = u.pm * 256 + wr * 64 + fr, col0 = u.pn * 256 + wc * 32 + 4 * fq;
; #pragma unroll
;         for (int ai = 0; ai < 2; ++ai)
; #pragma unroll
;             for (int m = 0; m < 4; ++m) { const bf16* sp = sel + (size_t)(row0 + ai * 128 + m * 16) * 3072 + (i - 1) * 1024 + col0;
; #pragma unroll
;                 for (int bj = 0; bj < 2; ++bj)
; #pragma unroll
;                     for (int n = 0; n < 2; ++n) { const u32x2 a = *(const u32x2*)(sp + bj * 128 + n * 16), b = *(const u32x2*)(sp + 1024 + bj * 128 + n * 16);
;                         f32x4 r; r[0] = bf2f(a.x & 0xffffu) * __builtin_amdgcn_rcpf(fmaxf(bf2f(b.x & 0xffffu), 1e-30f)); r[1] = bf2f(a.x >> 16) * __builtin_amdgcn_rcpf(fmaxf(bf2f(b.x >> 16), 1e-30f));
;                         r[2] = bf2f(a.y & 0xffffu) * __builtin_amdgcn_rcpf(fmaxf(bf2f(b.y & 0xffffu), 1e-30f)); r[3] = bf2f(a.y >> 16) * __builtin_amdgcn_rcpf(fmaxf(bf2f(b.y >> 16), 1e-30f));
;                         acc[ai][bj][m][n] = acc[ai][bj][m][n] * r; }
;                 asm volatile("" ::: "memory"); }
	v_lshlrev_b32_e32 v138, 16, v170
	v_and_b32_e32 v139, 0xffff0000, v170
	v_lshlrev_b32_e32 v140, 16, v171
	v_and_b32_e32 v141, 0xffff0000, v171
	v_max_f32_e32 v138, v138, v138
	v_max_f32_e32 v139, v139, v139
	v_max_f32_e32 v140, v140, v140
	v_max_f32_e32 v141, v141, v141
	v_max_f32_e32 v138, 0xda24260, v138
	v_max_f32_e32 v139, 0xda24260, v139
	v_max_f32_e32 v140, 0xda24260, v140
	v_max_f32_e32 v141, 0xda24260, v141
	v_rcp_f32_e32 v138, v138
	v_rcp_f32_e32 v139, v139
	v_rcp_f32_e32 v140, v140
	v_rcp_f32_e32 v141, v141
	v_lshlrev_b32_e32 v150, 16, v168
	v_and_b32_e32 v151, 0xffff0000, v168
	v_lshlrev_b32_e32 v152, 16, v169
	v_and_b32_e32 v153, 0xffff0000, v169
	v_pk_mul_f32 v[138:139], v[138:139], v[150:151]
	v_pk_mul_f32 v[140:141], v[140:141], v[152:153]
	v_pk_mul_f32 v[68:69], v[68:69], v[138:139]
	v_pk_mul_f32 v[70:71], v[70:71], v[140:141]
	s_waitcnt vmcnt(16)
	v_lshlrev_b32_e32 v138, 16, v174
	v_and_b32_e32 v139, 0xffff0000, v174
	v_lshlrev_b32_e32 v140, 16, v175
	v_and_b32_e32 v141, 0xffff0000, v175
	v_max_f32_e32 v138, v138, v138
	v_max_f32_e32 v139, v139, v139
	v_max_f32_e32 v140, v140, v140
	v_max_f32_e32 v141, v141, v141
	v_max_f32_e32 v138, 0xda24260, v138
	v_max_f32_e32 v139, 0xda24260, v139
	v_max_f32_e32 v140, 0xda24260, v140
	v_max_f32_e32 v141, 0xda24260, v141
	v_rcp_f32_e32 v138, v138
	v_rcp_f32_e32 v139, v139
	v_rcp_f32_e32 v140, v140
	v_rcp_f32_e32 v141, v141
	v_lshlrev_b32_e32 v150, 16, v172
	v_and_b32_e32 v151, 0xffff0000, v172
	v_lshlrev_b32_e32 v152, 16, v173
	v_and_b32_e32 v153, 0xffff0000, v173
	v_pk_mul_f32 v[138:139], v[138:139], v[150:151]
	v_pk_mul_f32 v[140:141], v[140:141], v[152:153]
	v_pk_mul_f32 v[64:65], v[64:65], v[138:139]
	v_pk_mul_f32 v[66:67], v[66:67], v[140:141]
	s_waitcnt vmcnt(14)
	v_lshlrev_b32_e32 v138, 16, v178
	v_and_b32_e32 v139, 0xffff0000, v178
	v_lshlrev_b32_e32 v140, 16, v179
	v_and_b32_e32 v141, 0xffff0000, v179
	v_max_f32_e32 v138, v138, v138
	v_max_f32_e32 v139, v139, v139
	v_max_f32_e32 v140, v140, v140
	v_max_f32_e32 v141, v141, v141
	v_max_f32_e32 v138, 0xda24260, v138
	v_max_f32_e32 v139, 0xda24260, v139
	v_max_f32_e32 v140, 0xda24260, v140
	v_max_f32_e32 v141, 0xda24260, v141
	v_rcp_f32_e32 v138, v138
	v_rcp_f32_e32 v139, v139
	v_rcp_f32_e32 v140, v140
	v_rcp_f32_e32 v141, v141
	v_lshlrev_b32_e32 v150, 16, v176
	v_and_b32_e32 v151, 0xffff0000, v176
	v_lshlrev_b32_e32 v152, 16, v177
	v_and_b32_e32 v153, 0xffff0000, v177
	v_pk_mul_f32 v[138:139], v[138:139], v[150:151]
	v_pk_mul_f32 v[140:141], v[140:141], v[152:153]
	v_pk_mul_f32 v[60:61], v[60:61], v[138:139]
	v_pk_mul_f32 v[62:63], v[62:63], v[140:141]
	s_waitcnt vmcnt(12)
	v_lshlrev_b32_e32 v138, 16, v182
	v_and_b32_e32 v139, 0xffff0000, v182
	v_lshlrev_b32_e32 v140, 16, v183
	v_and_b32_e32 v141, 0xffff0000, v183
	v_max_f32_e32 v138, v138, v138
	v_max_f32_e32 v139, v139, v139
	v_max_f32_e32 v140, v140, v140
	v_max_f32_e32 v141, v141, v141
	v_max_f32_e32 v138, 0xda24260, v138
	v_max_f32_e32 v139, 0xda24260, v139
	v_max_f32_e32 v140, 0xda24260, v140
	v_max_f32_e32 v141, 0xda24260, v141
	v_rcp_f32_e32 v138, v138
	v_rcp_f32_e32 v139, v139
	v_rcp_f32_e32 v140, v140
	v_rcp_f32_e32 v141, v141
	v_lshlrev_b32_e32 v150, 16, v180
	v_and_b32_e32 v151, 0xffff0000, v180
	v_lshlrev_b32_e32 v152, 16, v181
	v_and_b32_e32 v153, 0xffff0000, v181
	v_pk_mul_f32 v[138:139], v[138:139], v[150:151]
	v_pk_mul_f32 v[140:141], v[140:141], v[152:153]
	v_pk_mul_f32 v[56:57], v[56:57], v[138:139]
	v_pk_mul_f32 v[58:59], v[58:59], v[140:141]
	s_waitcnt vmcnt(10)
	v_lshlrev_b32_e32 v138, 16, v186
	v_and_b32_e32 v139, 0xffff0000, v186
	v_lshlrev_b32_e32 v140, 16, v187
	v_and_b32_e32 v141, 0xffff0000, v187
	v_max_f32_e32 v138, v138, v138
	v_max_f32_e32 v139, v139, v139
	v_max_f32_e32 v140, v140, v140
	v_max_f32_e32 v141, v141, v141
	v_max_f32_e32 v138, 0xda24260, v138
	v_max_f32_e32 v139, 0xda24260, v139
	v_max_f32_e32 v140, 0xda24260, v140
	v_max_f32_e32 v141, 0xda24260, v141
	v_rcp_f32_e32 v138, v138
	v_rcp_f32_e32 v139, v139
	v_rcp_f32_e32 v140, v140
	v_rcp_f32_e32 v141, v141
	v_lshlrev_b32_e32 v150, 16, v184
	v_and_b32_e32 v151, 0xffff0000, v184
	v_lshlrev_b32_e32 v152, 16, v185
	v_and_b32_e32 v153, 0xffff0000, v185
	v_pk_mul_f32 v[138:139], v[138:139], v[150:151]
	v_pk_mul_f32 v[140:141], v[140:141], v[152:153]
	v_pk_mul_f32 v[52:53], v[52:53], v[138:139]
	v_pk_mul_f32 v[54:55], v[54:55], v[140:141]
	s_waitcnt vmcnt(8)
	v_lshlrev_b32_e32 v138, 16, v190
	v_and_b32_e32 v139, 0xffff0000, v190
	v_lshlrev_b32_e32 v140, 16, v191
	v_and_b32_e32 v141, 0xffff0000, v191
	v_max_f32_e32 v138, v138, v138
	v_max_f32_e32 v139, v139, v139
	v_max_f32_e32 v140, v140, v140
	v_max_f32_e32 v141, v141, v141
	v_max_f32_e32 v138, 0xda24260, v138
	v_max_f32_e32 v139, 0xda24260, v139
	v_max_f32_e32 v140, 0xda24260, v140
	v_max_f32_e32 v141, 0xda24260, v141
	v_rcp_f32_e32 v138, v138
	v_rcp_f32_e32 v139, v139
	v_rcp_f32_e32 v140, v140
	v_rcp_f32_e32 v141, v141
	v_lshlrev_b32_e32 v150, 16, v188
	v_and_b32_e32 v151, 0xffff0000, v188
	v_lshlrev_b32_e32 v152, 16, v189
	v_and_b32_e32 v153, 0xffff0000, v189
	v_pk_mul_f32 v[138:139], v[138:139], v[150:151]
	v_pk_mul_f32 v[140:141], v[140:141], v[152:153]
	v_pk_mul_f32 v[48:49], v[48:49], v[138:139]
	v_pk_mul_f32 v[50:51], v[50:51], v[140:141]
	s_waitcnt vmcnt(6)
; __device__ __forceinline__ float bf2f(unsigned b) { return __uint_as_float(b << 16); }
;     __device__ __forceinline__ void operator()(f32x4 (&acc)[2][2][4][2], const pg8::Unit& u, int wr, int wc, int fr, int fq, int t) const {
;     ...
;         const int i = t >> 3;
;         const int row0 = u.pm * 256 + wr * 64 + fr, col0 = u.pn * 256 + wc * 32 + 4 * fq;
; #pragma unroll
;         for (int ai = 0; ai < 2; ++ai)
; #pragma unroll
;             for (int m = 0; m < 4; ++m) { const bf16* sp = sel + (size_t)(row0 + ai * 128 + m * 16) * 3072 + (i - 1) * 1024 + col0;
; #pragma unroll
;                 for (int bj = 0; bj < 2; ++bj)
; #pragma unroll
;                     for (int n = 0; n < 2; ++n) { const u32x2 a = *(const u32x2*)(sp + bj * 128 + n * 16), b = *(const u32x2*)(sp + 1024 + bj * 128 + n * 16);
;                         f32x4 r; r[0] = bf2f(a.x & 0xffffu) * __builtin_amdgcn_rcpf(fmaxf(bf2f(b.x & 0xffffu), 1e-30f)); r[1] = bf2f(a.x >> 16) * __builtin_amdgcn_rcpf(fmaxf(bf2f(b.x >> 16), 1e-30f));
;                         r[2] = bf2f(a.y & 0xffffu) * __builtin_amdgcn_rcpf(fmaxf(bf2f(b.y & 0xffffu), 1e-30f)); r[3] = bf2f(a.y >> 16) * __builtin_amdgcn_rcpf(fmaxf(bf2f(b.y >> 16), 1e-30f));
;                         acc[ai][bj][m][n] = acc[ai][bj][m][n] * r; }
;                 asm volatile("" ::: "memory"); }
	v_lshlrev_b32_e32 v138, 16, v194
	v_and_b32_e32 v139, 0xffff0000, v194
	v_lshlrev_b32_e32 v140, 16, v195
	v_and_b32_e32 v141, 0xffff0000, v195
	v_max_f32_e32 v138, v138, v138
	v_max_f32_e32 v139, v139, v139
	v_max_f32_e32 v140, v140, v140
	v_max_f32_e32 v141, v141, v141
	v_max_f32_e32 v138, 0xda24260, v138
	v_max_f32_e32 v139, 0xda24260, v139
	v_max_f32_e32 v140, 0xda24260, v140
	v_max_f32_e32 v141, 0xda24260, v141
	v_rcp_f32_e32 v138, v138
	v_rcp_f32_e32 v139, v139
	v_rcp_f32_e32 v140, v140
	v_rcp_f32_e32 v141, v141
	v_lshlrev_b32_e32 v150, 16, v192
	v_and_b32_e32 v151, 0xffff0000, v192
	v_lshlrev_b32_e32 v152, 16, v193
	v_and_b32_e32 v153, 0xffff0000, v193
	v_pk_mul_f32 v[138:139], v[138:139], v[150:151]
	v_pk_mul_f32 v[140:141], v[140:141], v[152:153]
	v_pk_mul_f32 v[44:45], v[44:45], v[138:139]
	v_pk_mul_f32 v[46:47], v[46:47], v[140:141]
	s_waitcnt vmcnt(4)
	v_lshlrev_b32_e32 v138, 16, v198
	v_and_b32_e32 v139, 0xffff0000, v198
	v_lshlrev_b32_e32 v140, 16, v199
	v_and_b32_e32 v141, 0xffff0000, v199
	v_max_f32_e32 v138, v138, v138
	v_max_f32_e32 v139, v139, v139
	v_max_f32_e32 v140, v140, v140
	v_max_f32_e32 v141, v141, v141
	v_max_f32_e32 v138, 0xda24260, v138
	v_max_f32_e32 v139, 0xda24260, v139
	v_max_f32_e32 v140, 0xda24260, v140
	v_max_f32_e32 v141, 0xda24260, v141
	v_rcp_f32_e32 v138, v138
	v_rcp_f32_e32 v139, v139
	v_rcp_f32_e32 v140, v140
	v_rcp_f32_e32 v141, v141
	v_lshlrev_b32_e32 v150, 16, v196
	v_and_b32_e32 v151, 0xffff0000, v196
	v_lshlrev_b32_e32 v152, 16, v197
	v_and_b32_e32 v153, 0xffff0000, v197
	v_pk_mul_f32 v[138:139], v[138:139], v[150:151]
	v_pk_mul_f32 v[140:141], v[140:141], v[152:153]
	v_pk_mul_f32 v[40:41], v[40:41], v[138:139]
	v_pk_mul_f32 v[42:43], v[42:43], v[140:141]
	s_waitcnt vmcnt(2)
	v_lshlrev_b32_e32 v138, 16, v202
	v_and_b32_e32 v139, 0xffff0000, v202
	v_lshlrev_b32_e32 v140, 16, v203
	v_and_b32_e32 v141, 0xffff0000, v203
	v_max_f32_e32 v138, v138, v138
	v_max_f32_e32 v139, v139, v139
	v_max_f32_e32 v140, v140, v140
	v_max_f32_e32 v141, v141, v141
	v_max_f32_e32 v138, 0xda24260, v138
	v_max_f32_e32 v139, 0xda24260, v139
	v_max_f32_e32 v140, 0xda24260, v140
	v_max_f32_e32 v141, 0xda24260, v141
	v_rcp_f32_e32 v138, v138
	v_rcp_f32_e32 v139, v139
	v_rcp_f32_e32 v140, v140
	v_rcp_f32_e32 v141, v141
	v_lshlrev_b32_e32 v150, 16, v200
	v_and_b32_e32 v151, 0xffff0000, v200
	v_lshlrev_b32_e32 v152, 16, v201
	v_and_b32_e32 v153, 0xffff0000, v201
	v_pk_mul_f32 v[138:139], v[138:139], v[150:151]
	v_pk_mul_f32 v[140:141], v[140:141], v[152:153]
	v_pk_mul_f32 v[36:37], v[36:37], v[138:139]
	v_pk_mul_f32 v[38:39], v[38:39], v[140:141]
	s_waitcnt vmcnt(0)
	v_lshlrev_b32_e32 v138, 16, v206
	v_and_b32_e32 v139, 0xffff0000, v206
	v_lshlrev_b32_e32 v140, 16, v207
	v_and_b32_e32 v141, 0xffff0000, v207
	v_max_f32_e32 v138, v138, v138
	v_max_f32_e32 v139, v139, v139
	v_max_f32_e32 v140, v140, v140
	v_max_f32_e32 v141, v141, v141
	v_max_f32_e32 v138, 0xda24260, v138
	v_max_f32_e32 v139, 0xda24260, v139
	v_max_f32_e32 v140, 0xda24260, v140
	v_max_f32_e32 v141, 0xda24260, v141
	v_rcp_f32_e32 v138, v138
	v_rcp_f32_e32 v139, v139
	v_rcp_f32_e32 v140, v140
	v_rcp_f32_e32 v141, v141
	v_lshlrev_b32_e32 v150, 16, v204
	v_and_b32_e32 v151, 0xffff0000, v204
	v_lshlrev_b32_e32 v152, 16, v205
	v_and_b32_e32 v153, 0xffff0000, v205
	v_pk_mul_f32 v[138:139], v[138:139], v[150:151]
	v_pk_mul_f32 v[140:141], v[140:141], v[152:153]
	v_pk_mul_f32 v[32:33], v[32:33], v[138:139]
	v_pk_mul_f32 v[34:35], v[34:35], v[140:141]
	v_add_u32_e32 v150, 160, v96
	v_mad_i64_i32 v[150:151], s[48:49], v150, s78, v[98:99]
	v_lshl_add_u64 v[150:151], v[150:151], 0, s[58:59]
	v_lshl_add_u64 v[150:151], v[150:151], 0, v[148:149]
	global_load_dwordx2 v[160:161], v[150:151], off
	global_load_dwordx2 v[162:163], v[150:151], off offset:2048
	global_load_dwordx2 v[164:165], v[150:151], off offset:32
	global_load_dwordx2 v[166:167], v[150:151], off offset:2080
	global_load_dwordx2 v[168:169], v[150:151], off offset:256
	global_load_dwordx2 v[170:171], v[150:151], off offset:2304
	global_load_dwordx2 v[172:173], v[150:151], off offset:288
	global_load_dwordx2 v[174:175], v[150:151], off offset:2336
	v_add_u32_e32 v150, 176, v96
	v_mad_i64_i32 v[150:151], s[48:49], v150, s78, v[98:99]
	v_lshl_add_u64 v[150:151], v[150:151], 0, s[58:59]
	v_lshl_add_u64 v[150:151], v[150:151], 0, v[148:149]
	global_load_dwordx2 v[176:177], v[150:151], off
	global_load_dwordx2 v[178:179], v[150:151], off offset:2048
	global_load_dwordx2 v[180:181], v[150:151], off offset:32
	global_load_dwordx2 v[182:183], v[150:151], off offset:2080
	global_load_dwordx2 v[184:185], v[150:151], off offset:256
	global_load_dwordx2 v[186:187], v[150:151], off offset:2304
	global_load_dwordx2 v[188:189], v[150:151], off offset:288
	global_load_dwordx2 v[190:191], v[150:151], off offset:2336
	s_waitcnt vmcnt(14)
	v_lshlrev_b32_e32 v138, 16, v162
	v_and_b32_e32 v139, 0xffff0000, v162
	v_lshlrev_b32_e32 v140, 16, v163
	v_and_b32_e32 v141, 0xffff0000, v163
	v_max_f32_e32 v138, v138, v138
	v_max_f32_e32 v139, v139, v139
	v_max_f32_e32 v140, v140, v140
	v_max_f32_e32 v141, v141, v141
	v_max_f32_e32 v138, 0xda24260, v138
	v_max_f32_e32 v139, 0xda24260, v139
	v_max_f32_e32 v140, 0xda24260, v140
	v_max_f32_e32 v141, 0xda24260, v141
	v_rcp_f32_e32 v138, v138
	v_rcp_f32_e32 v139, v139
	v_rcp_f32_e32 v140, v140
	v_rcp_f32_e32 v141, v141
	v_lshlrev_b32_e32 v150, 16, v160
	v_and_b32_e32 v151, 0xffff0000, v160
	v_lshlrev_b32_e32 v152, 16, v161
	v_and_b32_e32 v153, 0xffff0000, v161
	v_pk_mul_f32 v[138:139], v[138:139], v[150:151]
	v_pk_mul_f32 v[140:141], v[140:141], v[152:153]
	v_pk_mul_f32 v[28:29], v[28:29], v[138:139]
	v_pk_mul_f32 v[30:31], v[30:31], v[140:141]
	s_waitcnt vmcnt(12)
; __device__ __forceinline__ float bf2f(unsigned b) { return __uint_as_float(b << 16); }
;     __device__ __forceinline__ void operator()(f32x4 (&acc)[2][2][4][2], const pg8::Unit& u, int wr, int wc, int fr, int fq, int t) const {
;     ...
;         const int i = t >> 3;
;         const int row0 = u.pm * 256 + wr * 64 + fr, col0 = u.pn * 256 + wc * 32 + 4 * fq;
; #pragma unroll
;         for (int ai = 0; ai < 2; ++ai)
; #pragma unroll
;             for (int m = 0; m < 4; ++m) { const bf16* sp = sel + (size_t)(row0 + ai * 128 + m * 16) * 3072 + (i - 1) * 1024 + col0;
; #pragma unroll
;                 for (int bj = 0; bj < 2; ++bj)
; #pragma unroll
;                     for (int n = 0; n < 2; ++n) { const u32x2 a = *(const u32x2*)(sp + bj * 128 + n * 16), b = *(const u32x2*)(sp + 1024 + bj * 128 + n * 16);
;                         f32x4 r; r[0] = bf2f(a.x & 0xffffu) * __builtin_amdgcn_rcpf(fmaxf(bf2f(b.x & 0xffffu), 1e-30f)); r[1] = bf2f(a.x >> 16) * __builtin_amdgcn_rcpf(fmaxf(bf2f(b.x >> 16), 1e-30f));
;                         r[2] = bf2f(a.y & 0xffffu) * __builtin_amdgcn_rcpf(fmaxf(bf2f(b.y & 0xffffu), 1e-30f)); r[3] = bf2f(a.y >> 16) * __builtin_amdgcn_rcpf(fmaxf(bf2f(b.y >> 16), 1e-30f));
;                         acc[ai][bj][m][n] = acc[ai][bj][m][n] * r; }
;                 asm volatile("" ::: "memory"); }
	v_lshlrev_b32_e32 v138, 16, v166
	v_and_b32_e32 v139, 0xffff0000, v166
	v_lshlrev_b32_e32 v140, 16, v167
	v_and_b32_e32 v141, 0xffff0000, v167
	v_max_f32_e32 v138, v138, v138
	v_max_f32_e32 v139, v139, v139
	v_max_f32_e32 v140, v140, v140
	v_max_f32_e32 v141, v141, v141
	v_max_f32_e32 v138, 0xda24260, v138
	v_max_f32_e32 v139, 0xda24260, v139
	v_max_f32_e32 v140, 0xda24260, v140
	v_max_f32_e32 v141, 0xda24260, v141
	v_rcp_f32_e32 v138, v138
	v_rcp_f32_e32 v139, v139
	v_rcp_f32_e32 v140, v140
	v_rcp_f32_e32 v141, v141
	v_lshlrev_b32_e32 v150, 16, v164
	v_and_b32_e32 v151, 0xffff0000, v164
	v_lshlrev_b32_e32 v152, 16, v165
	v_and_b32_e32 v153, 0xffff0000, v165
	v_pk_mul_f32 v[138:139], v[138:139], v[150:151]
	v_pk_mul_f32 v[140:141], v[140:141], v[152:153]
	v_pk_mul_f32 v[24:25], v[24:25], v[138:139]
	v_pk_mul_f32 v[26:27], v[26:27], v[140:141]
	s_waitcnt vmcnt(10)
	v_lshlrev_b32_e32 v138, 16, v170
	v_and_b32_e32 v139, 0xffff0000, v170
	v_lshlrev_b32_e32 v140, 16, v171
	v_and_b32_e32 v141, 0xffff0000, v171
	v_max_f32_e32 v138, v138, v138
	v_max_f32_e32 v139, v139, v139
	v_max_f32_e32 v140, v140, v140
	v_max_f32_e32 v141, v141, v141
	v_max_f32_e32 v138, 0xda24260, v138
	v_max_f32_e32 v139, 0xda24260, v139
	v_max_f32_e32 v140, 0xda24260, v140
	v_max_f32_e32 v141, 0xda24260, v141
	v_rcp_f32_e32 v138, v138
	v_rcp_f32_e32 v139, v139
	v_rcp_f32_e32 v140, v140
	v_rcp_f32_e32 v141, v141
	v_lshlrev_b32_e32 v150, 16, v168
	v_and_b32_e32 v151, 0xffff0000, v168
	v_lshlrev_b32_e32 v152, 16, v169
	v_and_b32_e32 v153, 0xffff0000, v169
	v_pk_mul_f32 v[138:139], v[138:139], v[150:151]
	v_pk_mul_f32 v[140:141], v[140:141], v[152:153]
	v_pk_mul_f32 v[20:21], v[20:21], v[138:139]
	v_pk_mul_f32 v[22:23], v[22:23], v[140:141]
	s_waitcnt vmcnt(8)
	v_lshlrev_b32_e32 v138, 16, v174
	v_and_b32_e32 v139, 0xffff0000, v174
	v_lshlrev_b32_e32 v140, 16, v175
	v_and_b32_e32 v141, 0xffff0000, v175
	v_max_f32_e32 v138, v138, v138
	v_max_f32_e32 v139, v139, v139
	v_max_f32_e32 v140, v140, v140
	v_max_f32_e32 v141, v141, v141
	v_max_f32_e32 v138, 0xda24260, v138
	v_max_f32_e32 v139, 0xda24260, v139
	v_max_f32_e32 v140, 0xda24260, v140
	v_max_f32_e32 v141, 0xda24260, v141
	v_rcp_f32_e32 v138, v138
	v_rcp_f32_e32 v139, v139
	v_rcp_f32_e32 v140, v140
	v_rcp_f32_e32 v141, v141
	v_lshlrev_b32_e32 v150, 16, v172
	v_and_b32_e32 v151, 0xffff0000, v172
	v_lshlrev_b32_e32 v152, 16, v173
	v_and_b32_e32 v153, 0xffff0000, v173
	v_pk_mul_f32 v[138:139], v[138:139], v[150:151]
	v_pk_mul_f32 v[140:141], v[140:141], v[152:153]
	v_pk_mul_f32 v[16:17], v[16:17], v[138:139]
	v_pk_mul_f32 v[18:19], v[18:19], v[140:141]
	s_waitcnt vmcnt(6)
	v_lshlrev_b32_e32 v138, 16, v178
	v_and_b32_e32 v139, 0xffff0000, v178
	v_lshlrev_b32_e32 v140, 16, v179
	v_and_b32_e32 v141, 0xffff0000, v179
	v_max_f32_e32 v138, v138, v138
	v_max_f32_e32 v139, v139, v139
	v_max_f32_e32 v140, v140, v140
	v_max_f32_e32 v141, v141, v141
	v_max_f32_e32 v138, 0xda24260, v138
	v_max_f32_e32 v139, 0xda24260, v139
	v_max_f32_e32 v140, 0xda24260, v140
	v_max_f32_e32 v141, 0xda24260, v141
	v_rcp_f32_e32 v138, v138
	v_rcp_f32_e32 v139, v139
	v_rcp_f32_e32 v140, v140
	v_rcp_f32_e32 v141, v141
	v_lshlrev_b32_e32 v150, 16, v176
	v_and_b32_e32 v151, 0xffff0000, v176
	v_lshlrev_b32_e32 v152, 16, v177
	v_and_b32_e32 v153, 0xffff0000, v177
	v_pk_mul_f32 v[138:139], v[138:139], v[150:151]
	v_pk_mul_f32 v[140:141], v[140:141], v[152:153]
	v_pk_mul_f32 v[12:13], v[12:13], v[138:139]
	v_pk_mul_f32 v[14:15], v[14:15], v[140:141]
	s_waitcnt vmcnt(4)
	v_lshlrev_b32_e32 v138, 16, v182
	v_and_b32_e32 v139, 0xffff0000, v182
	v_lshlrev_b32_e32 v140, 16, v183
	v_and_b32_e32 v141, 0xffff0000, v183
	v_max_f32_e32 v138, v138, v138
	v_max_f32_e32 v139, v139, v139
	v_max_f32_e32 v140, v140, v140
	v_max_f32_e32 v141, v141, v141
	v_max_f32_e32 v138, 0xda24260, v138
	v_max_f32_e32 v139, 0xda24260, v139
	v_max_f32_e32 v140, 0xda24260, v140
	v_max_f32_e32 v141, 0xda24260, v141
	v_rcp_f32_e32 v138, v138
	v_rcp_f32_e32 v139, v139
	v_rcp_f32_e32 v140, v140
	v_rcp_f32_e32 v141, v141
	v_lshlrev_b32_e32 v150, 16, v180
	v_and_b32_e32 v151, 0xffff0000, v180
	v_lshlrev_b32_e32 v152, 16, v181
	v_and_b32_e32 v153, 0xffff0000, v181
	v_pk_mul_f32 v[138:139], v[138:139], v[150:151]
	v_pk_mul_f32 v[140:141], v[140:141], v[152:153]
	v_pk_mul_f32 v[8:9], v[8:9], v[138:139]
	v_pk_mul_f32 v[10:11], v[10:11], v[140:141]
	s_waitcnt vmcnt(2)
	v_lshlrev_b32_e32 v138, 16, v186
	v_and_b32_e32 v139, 0xffff0000, v186
	v_lshlrev_b32_e32 v140, 16, v187
	v_and_b32_e32 v141, 0xffff0000, v187
	v_max_f32_e32 v138, v138, v138
	v_max_f32_e32 v139, v139, v139
	v_max_f32_e32 v140, v140, v140
	v_max_f32_e32 v141, v141, v141
	v_max_f32_e32 v138, 0xda24260, v138
	v_max_f32_e32 v139, 0xda24260, v139
	v_max_f32_e32 v140, 0xda24260, v140
	v_max_f32_e32 v141, 0xda24260, v141
	v_rcp_f32_e32 v138, v138
	v_rcp_f32_e32 v139, v139
	v_rcp_f32_e32 v140, v140
	v_rcp_f32_e32 v141, v141
	v_lshlrev_b32_e32 v150, 16, v184
	v_and_b32_e32 v151, 0xffff0000, v184
	v_lshlrev_b32_e32 v152, 16, v185
	v_and_b32_e32 v153, 0xffff0000, v185
	v_pk_mul_f32 v[138:139], v[138:139], v[150:151]
	v_pk_mul_f32 v[140:141], v[140:141], v[152:153]
	v_pk_mul_f32 v[4:5], v[4:5], v[138:139]
	v_pk_mul_f32 v[6:7], v[6:7], v[140:141]
	s_waitcnt vmcnt(0)
	v_lshlrev_b32_e32 v138, 16, v190
	v_and_b32_e32 v139, 0xffff0000, v190
	v_lshlrev_b32_e32 v140, 16, v191
	v_and_b32_e32 v141, 0xffff0000, v191
	v_max_f32_e32 v138, v138, v138
	v_max_f32_e32 v139, v139, v139
	v_max_f32_e32 v140, v140, v140
	v_max_f32_e32 v141, v141, v141
	v_max_f32_e32 v138, 0xda24260, v138
	v_max_f32_e32 v139, 0xda24260, v139
	v_max_f32_e32 v140, 0xda24260, v140
	v_max_f32_e32 v141, 0xda24260, v141
	v_rcp_f32_e32 v138, v138
	v_rcp_f32_e32 v139, v139
	v_rcp_f32_e32 v140, v140
	v_rcp_f32_e32 v141, v141
	v_lshlrev_b32_e32 v150, 16, v188
	v_and_b32_e32 v151, 0xffff0000, v188
	v_lshlrev_b32_e32 v152, 16, v189
	v_and_b32_e32 v153, 0xffff0000, v189
	v_pk_mul_f32 v[138:139], v[138:139], v[150:151]
	v_pk_mul_f32 v[140:141], v[140:141], v[152:153]
	v_pk_mul_f32 v[0:1], v[0:1], v[138:139]
	v_pk_mul_f32 v[2:3], v[2:3], v[140:141]

; __device__ __forceinline__ float bf2f(unsigned b) { return __uint_as_float(b << 16); }
; __device__ __forceinline__ int crow(int r, int hi) { return (r & 3) + 8 * (r >> 2) + 4 * hi; }
; template <bool MERGE> __device__ __forceinline__ void ctx_mini_gemm(const Params& p, unsigned char* lds, int wid0) {
;     ...
;     for (int tile = blockIdx.x; tile < 256; tile += gridDim.x) {
;         const int rb = tile >> 4, cb = tile & 15; const size_t arow = (size_t)MLAT + 32 * rb + r32;
;         f32x16 tot[2];
; #pragma unroll
;         for (int c2 = 0; c2 < 2; ++c2)
; #pragma unroll
;             for (int r = 0; r < 16; ++r) tot[c2][r] = 0.f;
;         if (MERGE) {
;             const bf16* A = (const bf16*)(ws + WS_GATED) + arow * 1536 + 64 * wid + 8 * hi; const bf16* B = (const bf16*)(ws + WS_WBR) + (size_t)(64 * cb + r32) * 1536 + 64 * wid + 8 * hi;
;             const bf16* sel = (const bf16*)(ws + WS_SEL);
; #pragma unroll
;             for (int i = 0; i < 3; ++i) { f32x16 acc[2];
; #pragma unroll
;                 for (int c2 = 0; c2 < 2; ++c2)
; #pragma unroll
;                     for (int r = 0; r < 16; ++r) acc[c2][r] = 0.f;
; #pragma unroll
;                 for (int ks = 0; ks < 4; ++ks) { const bf16x8 a = *(const bf16x8*)(A + i * 512 + 16 * ks), b0 = *(const bf16x8*)(B + i * 512 + 16 * ks), b1 = *(const bf16x8*)(B + (size_t)32 * 1536 + i * 512 + 16 * ks);
;                     acc[0] = __builtin_amdgcn_mfma_f32_32x32x16_bf16(a, b0, acc[0], 0, 0, 0); acc[1] = __builtin_amdgcn_mfma_f32_32x32x16_bf16(a, b1, acc[1], 0, 0, 0); }
; #pragma unroll
;                 for (int c2 = 0; c2 < 2; ++c2)
; #pragma unroll
;                     for (int r = 0; r < 16; ++r) tot[c2][r] += acc[c2][r] * bf2f(sel[((size_t)MLAT + 32 * rb + crow(r, hi)) * 3072 + i * 1024 + 64 * cb + 32 * c2 + r32]); }
.LBB0_138:
	s_and_b32 s0, s34, 0xffffffe0
	s_ashr_i32 s1, s0, 31
	s_add_u32 s0, s0, 0x4000
	v_or_b32_e32 v0, s0, v32
	s_addc_u32 s1, s1, 0
	v_mad_u64_u32 v[110:111], s[40:41], v0, s90, v[34:35]
	v_mov_b32_e32 v0, 0xc00
	s_and_b32 s39, s35, 0x3c0
	v_mad_i32_i24 v111, s1, v0, v111
	v_or_b32_e32 v0, s39, v32
	v_mul_u32_u24_e32 v0, 0x600, v0
	v_lshlrev_b32_e32 v96, 1, v0
	v_lshl_add_u64 v[112:113], v[36:37], 0, v[96:97]
	v_add_co_u32_e32 v114, vcc, s75, v112
	global_load_dwordx4 v[0:3], v[110:111], off
	global_load_dwordx4 v[4:7], v[112:113], off
	v_addc_co_u32_e32 v115, vcc, 0, v113, vcc
	global_load_dwordx4 v[8:11], v[114:115], off
	global_load_dwordx4 v[76:79], v[110:111], off offset:32
	global_load_dwordx4 v[80:83], v[112:113], off offset:32
	global_load_dwordx4 v[84:87], v[114:115], off offset:32
	s_lshl_b32 s40, s39, 1
	s_mov_b32 s41, s92
	v_lshl_add_u64 v[74:75], v[40:41], 0, s[40:41]
	v_lshl_add_u64 v[88:89], s[0:1], 0, v[54:55]
	v_mad_u64_u32 v[174:175], s[40:41], v88, s78, v[74:75]
	v_mad_i32_i24 v175, v89, s78, v175
	v_lshl_add_u64 v[90:91], s[0:1], 0, v[56:57]
	v_mad_u64_u32 v[176:177], s[40:41], v90, s78, v[74:75]
	v_mad_i32_i24 v177, v91, s78, v177
	v_lshl_add_u64 v[92:93], s[0:1], 0, v[58:59]
	v_mad_u64_u32 v[178:179], s[40:41], v92, s78, v[74:75]
	v_mad_i32_i24 v179, v93, s78, v179
	v_lshl_add_u64 v[94:95], s[0:1], 0, v[60:61]
	v_mad_u64_u32 v[180:181], s[40:41], v94, s78, v[74:75]
	v_mad_i32_i24 v181, v95, s78, v181
	v_lshl_add_u64 v[98:99], s[0:1], 0, v[62:63]
	v_mad_u64_u32 v[182:183], s[40:41], v98, s78, v[74:75]
	v_mad_i32_i24 v183, v99, s78, v183
	v_lshl_add_u64 v[100:101], s[0:1], 0, v[64:65]
	v_mad_u64_u32 v[184:185], s[40:41], v100, s78, v[74:75]
	v_mad_i32_i24 v185, v101, s78, v185
	v_lshl_add_u64 v[102:103], s[0:1], 0, v[66:67]
	v_mad_u64_u32 v[186:187], s[40:41], v102, s78, v[74:75]
	v_mad_i32_i24 v187, v103, s78, v187
	v_lshl_add_u64 v[104:105], s[0:1], 0, v[68:69]
	v_mad_u64_u32 v[188:189], s[40:41], v104, s78, v[74:75]
	v_mad_i32_i24 v189, v105, s78, v189
	v_lshl_add_u64 v[106:107], s[0:1], 0, v[70:71]
	v_mad_u64_u32 v[190:191], s[40:41], v106, s78, v[74:75]
	v_mad_i32_i24 v191, v107, s78, v191
	v_lshl_add_u64 v[108:109], s[0:1], 0, v[72:73]
	v_mad_u64_u32 v[192:193], s[40:41], v108, s78, v[74:75]
	v_mad_i32_i24 v193, v109, s78, v193
	s_add_i32 s38, s38, s24
	s_add_i32 s35, s35, s26
	s_add_i32 s34, s34, s27
	s_cmpk_lt_i32 s38, 0x100
	s_waitcnt vmcnt(4)
	v_mfma_f32_32x32x16_bf16 v[16:31], v[0:3], v[4:7], 0
	s_waitcnt vmcnt(3)
	v_mfma_f32_32x32x16_bf16 v[0:15], v[0:3], v[8:11], 0
	s_waitcnt vmcnt(1)
	v_mfma_f32_32x32x16_bf16 v[16:31], v[76:79], v[80:83], v[16:31]
	s_waitcnt vmcnt(0)
	v_mfma_f32_32x32x16_bf16 v[0:15], v[76:79], v[84:87], v[0:15]
	global_load_dwordx4 v[76:79], v[110:111], off offset:64
	global_load_dwordx4 v[80:83], v[112:113], off offset:64
	global_load_dwordx4 v[84:87], v[114:115], off offset:64
	s_waitcnt vmcnt(1)
	v_mfma_f32_32x32x16_bf16 v[16:31], v[76:79], v[80:83], v[16:31]
	s_waitcnt vmcnt(0)
	v_mfma_f32_32x32x16_bf16 v[0:15], v[76:79], v[84:87], v[0:15]
	global_load_dwordx4 v[76:79], v[110:111], off offset:96
	global_load_dwordx4 v[80:83], v[112:113], off offset:96
	global_load_dwordx4 v[84:87], v[114:115], off offset:96
	s_waitcnt vmcnt(1)
	v_mfma_f32_32x32x16_bf16 v[16:31], v[76:79], v[80:83], v[16:31]
	s_waitcnt vmcnt(0)
	v_mfma_f32_32x32x16_bf16 v[0:15], v[76:79], v[84:87], v[0:15]
	v_lshl_add_u64 v[80:81], s[0:1], 0, v[46:47]
	v_mad_u64_u32 v[166:167], s[40:41], v80, s78, v[74:75]
	v_mad_i32_i24 v167, v81, s78, v167
	v_lshl_add_u64 v[82:83], s[0:1], 0, v[48:49]
	v_mad_u64_u32 v[168:169], s[40:41], v82, s78, v[74:75]
	v_lshl_add_u64 v[76:77], s[0:1], 0, v[38:39]
	v_mad_u64_u32 v[162:163], s[40:41], v76, s78, v[74:75]
	v_mad_i32_i24 v163, v77, s78, v163
	v_mad_i32_i24 v169, v83, s78, v169
	v_lshl_add_u64 v[84:85], s[0:1], 0, v[50:51]
	v_mad_u64_u32 v[170:171], s[40:41], v84, s78, v[74:75]
	v_mad_i32_i24 v171, v85, s78, v171
	v_lshl_add_u64 v[86:87], s[0:1], 0, v[52:53]
	v_mad_u64_u32 v[172:173], s[40:41], v86, s78, v[74:75]
	v_mad_i32_i24 v173, v87, s78, v173
	v_lshl_add_u64 v[78:79], s[0:1], 0, v[44:45]
	v_mad_u64_u32 v[164:165], s[40:41], v78, s78, v[74:75]
	v_mad_i32_i24 v165, v79, s78, v165
	global_load_ushort v194, v[162:163], off
	global_load_ushort v195, v[164:165], off
	global_load_ushort v196, v[166:167], off
	global_load_ushort v197, v[168:169], off
	global_load_ushort v198, v[170:171], off
	global_load_ushort v199, v[172:173], off
	global_load_ushort v200, v[174:175], off
	global_load_ushort v201, v[176:177], off
	global_load_ushort v202, v[178:179], off
	global_load_ushort v203, v[180:181], off
	global_load_ushort v204, v[182:183], off
	global_load_ushort v205, v[184:185], off
	global_load_ushort v206, v[186:187], off
	global_load_ushort v207, v[188:189], off
	global_load_ushort v208, v[190:191], off
	global_load_ushort v209, v[192:193], off
	global_load_ushort v234, v[162:163], off offset:64
	global_load_ushort v235, v[164:165], off offset:64
	global_load_ushort v236, v[166:167], off offset:64
	global_load_ushort v237, v[168:169], off offset:64
	global_load_ushort v238, v[170:171], off offset:64
	global_load_ushort v239, v[172:173], off offset:64
	global_load_ushort v240, v[174:175], off offset:64
	global_load_ushort v241, v[176:177], off offset:64
	global_load_ushort v242, v[178:179], off offset:64
	global_load_ushort v243, v[180:181], off offset:64
	global_load_ushort v244, v[182:183], off offset:64
	global_load_ushort v245, v[184:185], off offset:64
	global_load_ushort v246, v[186:187], off offset:64
	global_load_ushort v247, v[188:189], off offset:64
	global_load_ushort v248, v[190:191], off offset:64
	global_load_ushort v249, v[192:193], off offset:64
	s_waitcnt vmcnt(0)
; __device__ __forceinline__ float bf2f(unsigned b) { return __uint_as_float(b << 16); }
; __device__ __forceinline__ int crow(int r, int hi) { return (r & 3) + 8 * (r >> 2) + 4 * hi; }
; template <bool MERGE> __device__ __forceinline__ void ctx_mini_gemm(const Params& p, unsigned char* lds, int wid0) {
;     ...
;             for (int i = 0; i < 3; ++i) { f32x16 acc[2];
; #pragma unroll
;                 for (int c2 = 0; c2 < 2; ++c2)
; #pragma unroll
;                     for (int r = 0; r < 16; ++r) acc[c2][r] = 0.f;
; #pragma unroll
;                 for (int ks = 0; ks < 4; ++ks) { const bf16x8 a = *(const bf16x8*)(A + i * 512 + 16 * ks), b0 = *(const bf16x8*)(B + i * 512 + 16 * ks), b1 = *(const bf16x8*)(B + (size_t)32 * 1536 + i * 512 + 16 * ks);
;                     acc[0] = __builtin_amdgcn_mfma_f32_32x32x16_bf16(a, b0, acc[0], 0, 0, 0); acc[1] = __builtin_amdgcn_mfma_f32_32x32x16_bf16(a, b1, acc[1], 0, 0, 0); }
; #pragma unroll
;                 for (int c2 = 0; c2 < 2; ++c2)
; #pragma unroll
;                     for (int r = 0; r < 16; ++r) tot[c2][r] += acc[c2][r] * bf2f(sel[((size_t)MLAT + 32 * rb + crow(r, hi)) * 3072 + i * 1024 + 64 * cb + 32 * c2 + r32]); }
	v_lshlrev_b32_e32 v194, 16, v194
	v_fma_f32 v96, v16, v194, 0
	v_lshlrev_b32_e32 v195, 16, v195
	v_fma_f32 v118, v17, v195, 0
	v_lshlrev_b32_e32 v196, 16, v196
	v_fma_f32 v119, v18, v196, 0
	v_lshlrev_b32_e32 v197, 16, v197
	v_fma_f32 v120, v19, v197, 0
	v_lshlrev_b32_e32 v198, 16, v198
	v_fma_f32 v121, v20, v198, 0
	v_lshlrev_b32_e32 v199, 16, v199
	v_fma_f32 v122, v21, v199, 0
	v_lshlrev_b32_e32 v200, 16, v200
	v_fma_f32 v123, v22, v200, 0
	v_lshlrev_b32_e32 v201, 16, v201
	v_fma_f32 v124, v23, v201, 0
	v_lshlrev_b32_e32 v202, 16, v202
	v_fma_f32 v125, v24, v202, 0
	v_lshlrev_b32_e32 v203, 16, v203
	v_fma_f32 v126, v25, v203, 0
	v_lshlrev_b32_e32 v204, 16, v204
	v_fma_f32 v127, v26, v204, 0
	v_lshlrev_b32_e32 v205, 16, v205
	v_fma_f32 v128, v27, v205, 0
	v_lshlrev_b32_e32 v206, 16, v206
	v_fma_f32 v129, v28, v206, 0
	v_lshlrev_b32_e32 v207, 16, v207
	v_fma_f32 v130, v29, v207, 0
	v_lshlrev_b32_e32 v208, 16, v208
	v_fma_f32 v131, v30, v208, 0
	v_lshlrev_b32_e32 v209, 16, v209
	v_fma_f32 v132, v31, v209, 0
	v_lshlrev_b32_e32 v234, 16, v234
	v_fma_f32 v133, v0, v234, 0
	v_lshlrev_b32_e32 v235, 16, v235
	v_fma_f32 v134, v1, v235, 0
	v_lshlrev_b32_e32 v236, 16, v236
	v_fma_f32 v135, v2, v236, 0
	v_lshlrev_b32_e32 v237, 16, v237
	v_fma_f32 v136, v3, v237, 0
	v_lshlrev_b32_e32 v238, 16, v238
	v_fma_f32 v137, v4, v238, 0
	v_lshlrev_b32_e32 v239, 16, v239
	v_fma_f32 v142, v5, v239, 0
	v_lshlrev_b32_e32 v240, 16, v240
	v_fma_f32 v143, v6, v240, 0
	v_lshlrev_b32_e32 v241, 16, v241
	v_fma_f32 v144, v7, v241, 0
	v_lshlrev_b32_e32 v242, 16, v242
	v_fma_f32 v145, v8, v242, 0
	v_lshlrev_b32_e32 v243, 16, v243
	v_fma_f32 v146, v9, v243, 0
	v_lshlrev_b32_e32 v244, 16, v244
	v_fma_f32 v147, v10, v244, 0
	v_lshlrev_b32_e32 v245, 16, v245
	v_fma_f32 v148, v11, v245, 0
	v_lshlrev_b32_e32 v246, 16, v246
	v_fma_f32 v149, v12, v246, 0
	v_lshlrev_b32_e32 v247, 16, v247
	v_fma_f32 v150, v13, v247, 0
	v_lshlrev_b32_e32 v248, 16, v248
	v_fma_f32 v151, v14, v248, 0
	v_lshlrev_b32_e32 v249, 16, v249
	v_fma_f32 v152, v15, v249, 0
	global_load_dwordx4 v[0:3], v[110:111], off offset:1024
	global_load_dwordx4 v[4:7], v[112:113], off offset:1024
	global_load_dwordx4 v[8:11], v[114:115], off offset:1024
	global_load_dwordx4 v[138:141], v[110:111], off offset:1056
	global_load_dwordx4 v[154:157], v[112:113], off offset:1056
	global_load_dwordx4 v[158:161], v[114:115], off offset:1056
	s_waitcnt vmcnt(4)
	v_mfma_f32_32x32x16_bf16 v[16:31], v[0:3], v[4:7], 0
	s_waitcnt vmcnt(3)
	v_mfma_f32_32x32x16_bf16 v[0:15], v[0:3], v[8:11], 0
	s_waitcnt vmcnt(1)
	v_mfma_f32_32x32x16_bf16 v[16:31], v[138:141], v[154:157], v[16:31]
	s_waitcnt vmcnt(0)
	v_mfma_f32_32x32x16_bf16 v[0:15], v[138:141], v[158:161], v[0:15]
	global_load_dwordx4 v[138:141], v[110:111], off offset:1088
	global_load_dwordx4 v[154:157], v[112:113], off offset:1088
	global_load_dwordx4 v[158:161], v[114:115], off offset:1088
	s_waitcnt vmcnt(1)
	v_mfma_f32_32x32x16_bf16 v[16:31], v[138:141], v[154:157], v[16:31]
	s_waitcnt vmcnt(0)
	v_mfma_f32_32x32x16_bf16 v[0:15], v[138:141], v[158:161], v[0:15]
	global_load_dwordx4 v[138:141], v[110:111], off offset:1120
	global_load_dwordx4 v[154:157], v[112:113], off offset:1120
	global_load_dwordx4 v[158:161], v[114:115], off offset:1120
	s_waitcnt vmcnt(1)
	v_mfma_f32_32x32x16_bf16 v[16:31], v[138:141], v[154:157], v[16:31]
	s_waitcnt vmcnt(0)
	v_mfma_f32_32x32x16_bf16 v[0:15], v[138:141], v[158:161], v[0:15]
	global_load_ushort v194, v[162:163], off offset:2048
	global_load_ushort v195, v[164:165], off offset:2048
	global_load_ushort v196, v[166:167], off offset:2048
	global_load_ushort v197, v[168:169], off offset:2048
	global_load_ushort v198, v[170:171], off offset:2048
	global_load_ushort v199, v[172:173], off offset:2048
	global_load_ushort v200, v[174:175], off offset:2048
	global_load_ushort v201, v[176:177], off offset:2048
	global_load_ushort v202, v[178:179], off offset:2048
	global_load_ushort v203, v[180:181], off offset:2048
	global_load_ushort v204, v[182:183], off offset:2048
	global_load_ushort v205, v[184:185], off offset:2048
	global_load_ushort v206, v[186:187], off offset:2048
	global_load_ushort v207, v[188:189], off offset:2048
	global_load_ushort v208, v[190:191], off offset:2048
	global_load_ushort v209, v[192:193], off offset:2048
	global_load_ushort v234, v[162:163], off offset:2112
	global_load_ushort v235, v[164:165], off offset:2112
	global_load_ushort v236, v[166:167], off offset:2112
	global_load_ushort v237, v[168:169], off offset:2112
	global_load_ushort v238, v[170:171], off offset:2112
	global_load_ushort v239, v[172:173], off offset:2112
	global_load_ushort v240, v[174:175], off offset:2112
	global_load_ushort v241, v[176:177], off offset:2112
	global_load_ushort v242, v[178:179], off offset:2112
	global_load_ushort v243, v[180:181], off offset:2112
	global_load_ushort v244, v[182:183], off offset:2112
	global_load_ushort v245, v[184:185], off offset:2112
	global_load_ushort v246, v[186:187], off offset:2112
	global_load_ushort v247, v[188:189], off offset:2112
	global_load_ushort v248, v[190:191], off offset:2112
	global_load_ushort v249, v[192:193], off offset:2112
	s_waitcnt vmcnt(0)
; __device__ __forceinline__ float bf2f(unsigned b) { return __uint_as_float(b << 16); }
; __device__ __forceinline__ int crow(int r, int hi) { return (r & 3) + 8 * (r >> 2) + 4 * hi; }
; template <bool MERGE> __device__ __forceinline__ void ctx_mini_gemm(const Params& p, unsigned char* lds, int wid0) {
;     ...
;             for (int i = 0; i < 3; ++i) { f32x16 acc[2];
; #pragma unroll
;                 for (int c2 = 0; c2 < 2; ++c2)
; #pragma unroll
;                     for (int r = 0; r < 16; ++r) acc[c2][r] = 0.f;
; #pragma unroll
;                 for (int ks = 0; ks < 4; ++ks) { const bf16x8 a = *(const bf16x8*)(A + i * 512 + 16 * ks), b0 = *(const bf16x8*)(B + i * 512 + 16 * ks), b1 = *(const bf16x8*)(B + (size_t)32 * 1536 + i * 512 + 16 * ks);
;                     acc[0] = __builtin_amdgcn_mfma_f32_32x32x16_bf16(a, b0, acc[0], 0, 0, 0); acc[1] = __builtin_amdgcn_mfma_f32_32x32x16_bf16(a, b1, acc[1], 0, 0, 0); }
; #pragma unroll
;                 for (int c2 = 0; c2 < 2; ++c2)
; #pragma unroll
;                     for (int r = 0; r < 16; ++r) tot[c2][r] += acc[c2][r] * bf2f(sel[((size_t)MLAT + 32 * rb + crow(r, hi)) * 3072 + i * 1024 + 64 * cb + 32 * c2 + r32]); }
	v_lshlrev_b32_e32 v194, 16, v194
	v_fmac_f32_e32 v96, v16, v194
	v_lshlrev_b32_e32 v195, 16, v195
	v_fmac_f32_e32 v118, v17, v195
	v_lshlrev_b32_e32 v196, 16, v196
	v_fmac_f32_e32 v119, v18, v196
	v_lshlrev_b32_e32 v197, 16, v197
	v_fmac_f32_e32 v120, v19, v197
	v_lshlrev_b32_e32 v198, 16, v198
	v_fmac_f32_e32 v121, v20, v198
	v_lshlrev_b32_e32 v199, 16, v199
	v_fmac_f32_e32 v122, v21, v199
	v_lshlrev_b32_e32 v200, 16, v200
	v_fmac_f32_e32 v123, v22, v200
	v_lshlrev_b32_e32 v201, 16, v201
	v_fmac_f32_e32 v124, v23, v201
	v_lshlrev_b32_e32 v202, 16, v202
	v_fmac_f32_e32 v125, v24, v202
	v_lshlrev_b32_e32 v203, 16, v203
	v_fmac_f32_e32 v126, v25, v203
	v_lshlrev_b32_e32 v204, 16, v204
	v_fmac_f32_e32 v127, v26, v204
	v_lshlrev_b32_e32 v205, 16, v205
	v_fmac_f32_e32 v128, v27, v205
	v_lshlrev_b32_e32 v206, 16, v206
	v_fmac_f32_e32 v129, v28, v206
	v_lshlrev_b32_e32 v207, 16, v207
	v_fmac_f32_e32 v130, v29, v207
	v_lshlrev_b32_e32 v208, 16, v208
	v_fmac_f32_e32 v131, v30, v208
	v_lshlrev_b32_e32 v209, 16, v209
	v_fmac_f32_e32 v132, v31, v209
	v_lshlrev_b32_e32 v234, 16, v234
	v_fmac_f32_e32 v133, v0, v234
	v_lshlrev_b32_e32 v235, 16, v235
	v_fmac_f32_e32 v134, v1, v235
	v_lshlrev_b32_e32 v236, 16, v236
	v_fmac_f32_e32 v135, v2, v236
	v_lshlrev_b32_e32 v237, 16, v237
	v_fmac_f32_e32 v136, v3, v237
	v_lshlrev_b32_e32 v238, 16, v238
	v_fmac_f32_e32 v137, v4, v238
	v_lshlrev_b32_e32 v239, 16, v239
	v_fmac_f32_e32 v142, v5, v239
	v_lshlrev_b32_e32 v240, 16, v240
	v_fmac_f32_e32 v143, v6, v240
	v_lshlrev_b32_e32 v241, 16, v241
	v_fmac_f32_e32 v144, v7, v241
	v_lshlrev_b32_e32 v242, 16, v242
	v_fmac_f32_e32 v145, v8, v242
	v_lshlrev_b32_e32 v243, 16, v243
	v_fmac_f32_e32 v146, v9, v243
	v_lshlrev_b32_e32 v244, 16, v244
	v_fmac_f32_e32 v147, v10, v244
	v_lshlrev_b32_e32 v245, 16, v245
	v_fmac_f32_e32 v148, v11, v245
	v_lshlrev_b32_e32 v246, 16, v246
	v_fmac_f32_e32 v149, v12, v246
	v_lshlrev_b32_e32 v247, 16, v247
	v_fmac_f32_e32 v150, v13, v247
	v_lshlrev_b32_e32 v248, 16, v248
	v_fmac_f32_e32 v151, v14, v248
	v_lshlrev_b32_e32 v249, 16, v249
	v_fmac_f32_e32 v152, v15, v249
	global_load_dwordx4 v[0:3], v[110:111], off offset:2048
	global_load_dwordx4 v[4:7], v[112:113], off offset:2048
	global_load_dwordx4 v[8:11], v[114:115], off offset:2048
	global_load_dwordx4 v[138:141], v[110:111], off offset:2080
	global_load_dwordx4 v[154:157], v[112:113], off offset:2080
	global_load_dwordx4 v[158:161], v[114:115], off offset:2080
	s_waitcnt vmcnt(4)
	v_mfma_f32_32x32x16_bf16 v[16:31], v[0:3], v[4:7], 0
	s_waitcnt vmcnt(3)
	v_mfma_f32_32x32x16_bf16 v[0:15], v[0:3], v[8:11], 0
	s_waitcnt vmcnt(1)
	v_mfma_f32_32x32x16_bf16 v[16:31], v[138:141], v[154:157], v[16:31]
	s_waitcnt vmcnt(0)
	v_mfma_f32_32x32x16_bf16 v[0:15], v[138:141], v[158:161], v[0:15]
	global_load_dwordx4 v[138:141], v[110:111], off offset:2112
	global_load_dwordx4 v[154:157], v[112:113], off offset:2112
	global_load_dwordx4 v[158:161], v[114:115], off offset:2112
	s_waitcnt vmcnt(1)
	v_mfma_f32_32x32x16_bf16 v[16:31], v[138:141], v[154:157], v[16:31]
	s_waitcnt vmcnt(0)
	v_mfma_f32_32x32x16_bf16 v[0:15], v[138:141], v[158:161], v[0:15]
	global_load_dwordx4 v[138:141], v[110:111], off offset:2144
	s_nop 0
	global_load_dwordx4 v[110:113], v[112:113], off offset:2144
	s_nop 0
	global_load_dwordx4 v[154:157], v[114:115], off offset:2144
	s_waitcnt vmcnt(1)
	v_mfma_f32_32x32x16_bf16 v[16:31], v[138:141], v[110:113], v[16:31]
	s_waitcnt vmcnt(0)
	v_mfma_f32_32x32x16_bf16 v[0:15], v[138:141], v[154:157], v[0:15]
	s_mov_b64 vcc, 0x1000
	v_lshl_add_u64 v[162:163], v[162:163], 0, vcc
	v_lshl_add_u64 v[164:165], v[164:165], 0, vcc
	v_lshl_add_u64 v[166:167], v[166:167], 0, vcc
	v_lshl_add_u64 v[168:169], v[168:169], 0, vcc
	v_lshl_add_u64 v[170:171], v[170:171], 0, vcc
	v_lshl_add_u64 v[172:173], v[172:173], 0, vcc
	v_lshl_add_u64 v[174:175], v[174:175], 0, vcc
	v_lshl_add_u64 v[176:177], v[176:177], 0, vcc
	v_lshl_add_u64 v[178:179], v[178:179], 0, vcc
	v_lshl_add_u64 v[180:181], v[180:181], 0, vcc
	v_lshl_add_u64 v[182:183], v[182:183], 0, vcc
	v_lshl_add_u64 v[184:185], v[184:185], 0, vcc
	v_lshl_add_u64 v[186:187], v[186:187], 0, vcc
	v_lshl_add_u64 v[188:189], v[188:189], 0, vcc
	v_lshl_add_u64 v[190:191], v[190:191], 0, vcc
	v_lshl_add_u64 v[192:193], v[192:193], 0, vcc
	global_load_ushort v194, v[162:163], off
	global_load_ushort v195, v[164:165], off
	global_load_ushort v196, v[166:167], off
	global_load_ushort v197, v[168:169], off
	global_load_ushort v198, v[170:171], off
	global_load_ushort v199, v[172:173], off
	global_load_ushort v200, v[174:175], off
	global_load_ushort v201, v[176:177], off
	global_load_ushort v202, v[178:179], off
	global_load_ushort v203, v[180:181], off
	global_load_ushort v204, v[182:183], off
	global_load_ushort v205, v[184:185], off
	global_load_ushort v206, v[186:187], off
	global_load_ushort v207, v[188:189], off
	global_load_ushort v208, v[190:191], off
	global_load_ushort v209, v[192:193], off
	global_load_ushort v234, v[162:163], off offset:64
	global_load_ushort v235, v[164:165], off offset:64
	global_load_ushort v236, v[166:167], off offset:64
	global_load_ushort v237, v[168:169], off offset:64
	global_load_ushort v238, v[170:171], off offset:64
	global_load_ushort v239, v[172:173], off offset:64
	global_load_ushort v240, v[174:175], off offset:64
	global_load_ushort v241, v[176:177], off offset:64
	global_load_ushort v242, v[178:179], off offset:64
	global_load_ushort v243, v[180:181], off offset:64
	global_load_ushort v244, v[182:183], off offset:64
	global_load_ushort v245, v[184:185], off offset:64
	global_load_ushort v246, v[186:187], off offset:64
	global_load_ushort v247, v[188:189], off offset:64
	global_load_ushort v248, v[190:191], off offset:64
	global_load_ushort v249, v[192:193], off offset:64
	s_waitcnt vmcnt(0)
; __device__ __forceinline__ unsigned cvt_pk_bf16(float lo, float hi) { unsigned r; asm volatile("v_cvt_pk_bf16_f32 %0, %1, %2" : "=v"(r) : "v"(lo), "v"(hi)); return r; }
; __device__ __forceinline__ float bf2f(unsigned b) { return __uint_as_float(b << 16); }
; __device__ __forceinline__ int crow(int r, int hi) { return (r & 3) + 8 * (r >> 2) + 4 * hi; }
; template <bool MERGE> __device__ __forceinline__ void ctx_mini_gemm(const Params& p, unsigned char* lds, int wid0) {
;     ...
;                 for (int c2 = 0; c2 < 2; ++c2)
; #pragma unroll
;                     for (int r = 0; r < 16; ++r) tot[c2][r] += acc[c2][r] * bf2f(sel[((size_t)MLAT + 32 * rb + crow(r, hi)) * 3072 + i * 1024 + 64 * cb + 32 * c2 + r32]); }
;         } else {
;             const bf16* A = (const bf16*)(ws + WS_OUTPRE) + arow * 1024 + 128 * wid + 8 * hi; const bf16* B = (const bf16*)(ws + WS_WOUT) + (size_t)(64 * cb + r32) * 1024 + 128 * wid + 8 * hi;
; #pragma unroll
;             for (int ks = 0; ks < 8; ++ks) { const bf16x8 a = *(const bf16x8*)(A + 16 * ks), b0 = *(const bf16x8*)(B + 16 * ks), b1 = *(const bf16x8*)(B + (size_t)32 * 1024 + 16 * ks);
;                 tot[0] = __builtin_amdgcn_mfma_f32_32x32x16_bf16(a, b0, tot[0], 0, 0, 0); tot[1] = __builtin_amdgcn_mfma_f32_32x32x16_bf16(a, b1, tot[1], 0, 0, 0); }
;         }
; #pragma unroll
;         for (int c2 = 0; c2 < 2; ++c2)
; #pragma unroll
;             for (int r = 0; r < 16; ++r) part[(wid * 32 + crow(r, hi)) * 64 + 32 * c2 + r32] = tot[c2][r];
;         __syncthreads();
;         { const int e = 4 * tid, rr = e >> 6, cc = e & 63; f32x4 sum = *(const f32x4*)(part + e);
; #pragma unroll
;           for (int w = 1; w < 8; ++w) sum = sum + *(const f32x4*)(part + w * 2048 + e);
;           const size_t row = (size_t)MLAT + 32 * rb + rr; const int col = 64 * cb + cc;
;           if (MERGE) { u32x2 o; o.x = pg8::cvt_pk_bf16(sum[0], sum[1]); o.y = pg8::cvt_pk_bf16(sum[2], sum[3]); *(u32x2*)((bf16*)(ws + WS_OUTPRE) + row * 1024 + col) = o; }
;           else { u32x2 o; o.x = pg8::cvt_pk_bf16(sum[0], sum[1]); o.y = pg8::cvt_pk_bf16(sum[2], sum[3]); *(u32x2*)((bf16*)(ws + WS_OUT) + row * 1024 + col) = o; } }
;         __syncthreads();
	v_lshlrev_b32_e32 v194, 16, v194
	v_fmac_f32_e32 v96, v16, v194
	v_lshlrev_b32_e32 v195, 16, v195
	v_fmac_f32_e32 v118, v17, v195
	v_lshlrev_b32_e32 v196, 16, v196
	v_fmac_f32_e32 v119, v18, v196
	v_lshlrev_b32_e32 v197, 16, v197
	v_fmac_f32_e32 v120, v19, v197
	v_lshlrev_b32_e32 v198, 16, v198
	v_fmac_f32_e32 v121, v20, v198
	v_lshlrev_b32_e32 v199, 16, v199
	v_fmac_f32_e32 v122, v21, v199
	v_lshlrev_b32_e32 v200, 16, v200
	v_fmac_f32_e32 v123, v22, v200
	v_lshlrev_b32_e32 v201, 16, v201
	v_fmac_f32_e32 v124, v23, v201
	v_lshlrev_b32_e32 v202, 16, v202
	v_fmac_f32_e32 v125, v24, v202
	v_lshlrev_b32_e32 v203, 16, v203
	v_fmac_f32_e32 v126, v25, v203
	v_lshlrev_b32_e32 v204, 16, v204
	v_fmac_f32_e32 v127, v26, v204
	v_lshlrev_b32_e32 v205, 16, v205
	v_fmac_f32_e32 v128, v27, v205
	v_lshlrev_b32_e32 v206, 16, v206
	v_fmac_f32_e32 v129, v28, v206
	v_lshlrev_b32_e32 v207, 16, v207
	v_fmac_f32_e32 v130, v29, v207
	v_lshlrev_b32_e32 v208, 16, v208
	v_fmac_f32_e32 v131, v30, v208
	v_lshlrev_b32_e32 v209, 16, v209
	v_fmac_f32_e32 v132, v31, v209
	v_lshlrev_b32_e32 v234, 16, v234
	v_fmac_f32_e32 v133, v0, v234
	v_lshlrev_b32_e32 v235, 16, v235
	v_fmac_f32_e32 v134, v1, v235
	v_lshlrev_b32_e32 v236, 16, v236
	v_fmac_f32_e32 v135, v2, v236
	v_lshlrev_b32_e32 v237, 16, v237
	v_fmac_f32_e32 v136, v3, v237
	v_lshlrev_b32_e32 v238, 16, v238
	v_fmac_f32_e32 v137, v4, v238
	v_lshlrev_b32_e32 v239, 16, v239
	v_fmac_f32_e32 v142, v5, v239
	v_lshlrev_b32_e32 v240, 16, v240
	v_fmac_f32_e32 v143, v6, v240
	v_lshlrev_b32_e32 v241, 16, v241
	v_fmac_f32_e32 v144, v7, v241
	v_lshlrev_b32_e32 v242, 16, v242
	v_fmac_f32_e32 v145, v8, v242
	v_lshlrev_b32_e32 v243, 16, v243
	v_fmac_f32_e32 v146, v9, v243
	v_lshlrev_b32_e32 v244, 16, v244
	v_fmac_f32_e32 v147, v10, v244
	v_lshlrev_b32_e32 v245, 16, v245
	v_fmac_f32_e32 v148, v11, v245
	v_lshlrev_b32_e32 v246, 16, v246
	v_fmac_f32_e32 v149, v12, v246
	v_lshlrev_b32_e32 v247, 16, v247
	v_fmac_f32_e32 v150, v13, v247
	v_lshlrev_b32_e32 v248, 16, v248
	v_fmac_f32_e32 v151, v14, v248
	v_lshlrev_b32_e32 v249, 16, v249
	v_fmac_f32_e32 v152, v15, v249
	ds_write2_b32 v33, v96, v133 offset1:32
	ds_write2_b32 v33, v118, v134 offset0:64 offset1:96
	ds_write2_b32 v33, v119, v135 offset0:128 offset1:160
	ds_write2_b32 v33, v120, v136 offset0:192 offset1:224
	v_add_u32_e32 v0, 0x800, v33
	ds_write2_b32 v0, v121, v137 offset1:32
	ds_write2_b32 v0, v122, v142 offset0:64 offset1:96
	ds_write2_b32 v0, v123, v143 offset0:128 offset1:160
	ds_write2_b32 v0, v124, v144 offset0:192 offset1:224
	v_add_u32_e32 v0, 0x1000, v33
	ds_write2_b32 v0, v125, v145 offset1:32
	ds_write2_b32 v0, v126, v146 offset0:64 offset1:96
	ds_write2_b32 v0, v127, v147 offset0:128 offset1:160
	ds_write2_b32 v0, v128, v148 offset0:192 offset1:224
	v_add_u32_e32 v0, 0x1800, v33
	ds_write2_b32 v0, v129, v149 offset1:32
	ds_write2_b32 v0, v130, v150 offset0:64 offset1:96
	ds_write2_b32 v0, v131, v151 offset0:128 offset1:160
	ds_write2_b32 v0, v132, v152 offset0:192 offset1:224
	s_waitcnt lgkmcnt(0)
	s_barrier
	ds_read_b128 v[0:3], v117
	ds_read_b128 v[4:7], v117 offset:8192
	s_waitcnt lgkmcnt(0)
	v_pk_add_f32 v[6:7], v[2:3], v[6:7]
	v_pk_add_f32 v[4:5], v[0:1], v[4:5]
	ds_read_b128 v[0:3], v117 offset:16384
	s_waitcnt lgkmcnt(0)
	v_pk_add_f32 v[6:7], v[6:7], v[2:3]
	v_pk_add_f32 v[4:5], v[4:5], v[0:1]
	ds_read_b128 v[0:3], v117 offset:24576
	s_waitcnt lgkmcnt(0)
	v_pk_add_f32 v[6:7], v[6:7], v[2:3]
	v_pk_add_f32 v[4:5], v[4:5], v[0:1]
	ds_read_b128 v[0:3], v117 offset:32768
	s_waitcnt lgkmcnt(0)
	v_pk_add_f32 v[6:7], v[6:7], v[2:3]
	v_pk_add_f32 v[4:5], v[4:5], v[0:1]
	ds_read_b128 v[0:3], v117 offset:40960
	s_waitcnt lgkmcnt(0)
	v_pk_add_f32 v[6:7], v[6:7], v[2:3]
	v_pk_add_f32 v[4:5], v[4:5], v[0:1]
	ds_read_b128 v[0:3], v117 offset:49152
	s_waitcnt lgkmcnt(0)
	v_pk_add_f32 v[6:7], v[6:7], v[2:3]
	v_pk_add_f32 v[8:9], v[4:5], v[0:1]
	ds_read_b128 v[2:5], v117 offset:57344
	s_waitcnt lgkmcnt(0)
	v_pk_add_f32 v[0:1], v[6:7], v[4:5]
	v_pk_add_f32 v[4:5], v[8:9], v[2:3]
	v_lshl_add_u64 v[2:3], s[0:1], 0, v[42:43]
	v_or_b32_e32 v6, s39, v116
	v_cvt_pk_bf16_f32 v4, v4, v5
	v_cvt_pk_bf16_f32 v5, v0, v1
	v_lshlrev_b64 v[0:1], 11, v[2:3]
	v_lshl_add_u64 v[0:1], s[4:5], 0, v[0:1]
	v_lshlrev_b32_e32 v96, 1, v6
	v_lshl_add_u64 v[0:1], v[0:1], 0, v[96:97]
	global_store_dwordx2 v[0:1], v[4:5], off
	s_barrier
	s_cbranch_scc1 .LBB0_138

; __device__ __forceinline__ float bf2f(unsigned b) { return __uint_as_float(b << 16); }
; __device__ __forceinline__ void gmlp_item(const Params& p, int l, int row0, int hf, unsigned char* lds, int wid0) {
;     ...
;         u32x4 raw[8];
; #pragma unroll
;         for (int rr = 0; rr < 8; ++rr) raw[rr] = *(const u32x4*)(zgm + (size_t)(row0 + wid * 16 + hb * 8 + rr) * 1024 + 512 + 8 * lane);
;         float v[8][8], s[8];
; #pragma unroll
;         for (int rr = 0; rr < 8; ++rr) { v[rr][0] = bf2f(raw[rr].x & 0xffffu); v[rr][1] = bf2f(raw[rr].x >> 16); v[rr][2] = bf2f(raw[rr].y & 0xffffu); v[rr][3] = bf2f(raw[rr].y >> 16); v[rr][4] = bf2f(raw[rr].z & 0xffffu); v[rr][5] = bf2f(raw[rr].z >> 16); v[rr][6] = bf2f(raw[rr].w & 0xffffu); v[rr][7] = bf2f(raw[rr].w >> 16);
;             s[rr] = ((v[rr][0] + v[rr][1]) + (v[rr][2] + v[rr][3])) + ((v[rr][4] + v[rr][5]) + (v[rr][6] + v[rr][7])); }
; #pragma unroll
;         for (int rr = 0; rr < 8; ++rr) s[rr] = wave_sum(s[rr]) * (1.f / 512.f);
.LBB0_213:
	s_lshl_b32 s0, s46, 3
	s_or_b32 s0, s0, s45
	s_ashr_i32 s1, s0, 31
	s_lshl_b64 s[42:43], s[0:1], 11
	v_lshl_add_u64 v[18:19], v[16:17], 0, s[42:43]
	s_or_b32 s42, s0, 1
	s_ashr_i32 s43, s42, 31
	s_lshl_b64 s[42:43], s[42:43], 11
	v_lshl_add_u64 v[22:23], v[16:17], 0, s[42:43]
	s_or_b32 s42, s0, 2
	s_ashr_i32 s43, s42, 31
	s_lshl_b64 s[42:43], s[42:43], 11
	global_load_dwordx4 v[18:21], v[18:19], off offset:1024
	s_nop 0
	global_load_dwordx4 v[24:27], v[22:23], off offset:1024
	v_lshl_add_u64 v[22:23], v[16:17], 0, s[42:43]
	s_or_b32 s42, s0, 3
	s_ashr_i32 s43, s42, 31
	s_lshl_b64 s[42:43], s[42:43], 11
	global_load_dwordx4 v[34:37], v[22:23], off offset:1024
	v_lshl_add_u64 v[22:23], v[16:17], 0, s[42:43]
	s_or_b32 s42, s0, 4
	s_ashr_i32 s43, s42, 31
	s_lshl_b64 s[42:43], s[42:43], 11
	global_load_dwordx4 v[58:61], v[22:23], off offset:1024
	v_lshl_add_u64 v[22:23], v[16:17], 0, s[42:43]
	s_or_b32 s42, s0, 5
	s_ashr_i32 s43, s42, 31
	s_lshl_b64 s[42:43], s[42:43], 11
	global_load_dwordx4 v[62:65], v[22:23], off offset:1024
	v_lshl_add_u64 v[22:23], v[16:17], 0, s[42:43]
	global_load_dwordx4 v[66:69], v[22:23], off offset:1024
	s_or_b32 s42, s0, 6
	s_ashr_i32 s43, s42, 31
	s_or_b32 s0, s0, 7
	s_lshl_b64 s[42:43], s[42:43], 11
	s_ashr_i32 s1, s0, 31
	v_lshl_add_u64 v[22:23], v[16:17], 0, s[42:43]
	s_lshl_b64 s[0:1], s[0:1], 11
	global_load_dwordx4 v[70:73], v[22:23], off offset:1024
	v_lshl_add_u64 v[22:23], v[16:17], 0, s[0:1]
	global_load_dwordx4 v[74:77], v[22:23], off offset:1024
	s_waitcnt vmcnt(7)
	v_lshlrev_b32_e32 v46, 16, v18
	v_and_b32_e32 v42, 0xffff0000, v18
	v_lshlrev_b32_e32 v32, 16, v19
	v_and_b32_e32 v30, 0xffff0000, v19
	s_waitcnt vmcnt(6)
	v_lshlrev_b32_e32 v47, 16, v24
	v_and_b32_e32 v43, 0xffff0000, v24
	v_lshlrev_b32_e32 v33, 16, v25
	v_and_b32_e32 v31, 0xffff0000, v25
	v_lshlrev_b32_e32 v28, 16, v20
	v_and_b32_e32 v20, 0xffff0000, v20
	v_lshlrev_b32_e32 v18, 16, v21
	v_and_b32_e32 v22, 0xffff0000, v21
	v_lshlrev_b32_e32 v29, 16, v26
	v_and_b32_e32 v21, 0xffff0000, v26
	v_lshlrev_b32_e32 v19, 16, v27
	v_and_b32_e32 v23, 0xffff0000, v27
	s_waitcnt vmcnt(5)
	v_lshlrev_b32_e32 v56, 16, v34
	v_and_b32_e32 v52, 0xffff0000, v34
	v_lshlrev_b32_e32 v50, 16, v35
	v_and_b32_e32 v48, 0xffff0000, v35
	v_lshlrev_b32_e32 v34, 16, v37
	v_and_b32_e32 v26, 0xffff0000, v37
	s_waitcnt vmcnt(4)
	v_lshlrev_b32_e32 v57, 16, v58
	v_and_b32_e32 v53, 0xffff0000, v58
	v_lshlrev_b32_e32 v51, 16, v59
	v_and_b32_e32 v49, 0xffff0000, v59
	v_lshlrev_b32_e32 v39, 16, v60
	v_and_b32_e32 v37, 0xffff0000, v60
	v_lshlrev_b32_e32 v35, 16, v61
	v_and_b32_e32 v27, 0xffff0000, v61
	v_pk_add_f32 v[58:59], v[46:47], v[42:43]
	v_pk_add_f32 v[60:61], v[32:33], v[30:31]
	s_waitcnt vmcnt(3)
	v_lshlrev_b32_e32 v94, 16, v62
	s_waitcnt lgkmcnt(3)
	v_and_b32_e32 v92, 0xffff0000, v62
	v_lshlrev_b32_e32 v86, 16, v64
	v_and_b32_e32 v84, 0xffff0000, v64
	v_lshlrev_b32_e32 v80, 16, v65
	v_and_b32_e32 v62, 0xffff0000, v65
	v_pk_add_f32 v[58:59], v[58:59], v[60:61]
	v_pk_add_f32 v[60:61], v[28:29], v[20:21]
	v_pk_add_f32 v[64:65], v[18:19], v[22:23]
	v_lshlrev_b32_e32 v38, 16, v36
	v_and_b32_e32 v36, 0xffff0000, v36
	s_waitcnt vmcnt(2)
	v_lshlrev_b32_e32 v95, 16, v66
	s_waitcnt lgkmcnt(2)
	v_and_b32_e32 v93, 0xffff0000, v66
	v_lshlrev_b32_e32 v91, 16, v67
	v_and_b32_e32 v89, 0xffff0000, v67
	v_pk_add_f32 v[60:61], v[60:61], v[64:65]
	v_pk_add_f32 v[64:65], v[56:57], v[52:53]
	v_pk_add_f32 v[66:67], v[50:51], v[48:49]
	v_lshlrev_b32_e32 v90, 16, v63
	v_and_b32_e32 v88, 0xffff0000, v63
	v_lshlrev_b32_e32 v87, 16, v68
	v_and_b32_e32 v85, 0xffff0000, v68
	v_lshlrev_b32_e32 v81, 16, v69
	v_and_b32_e32 v63, 0xffff0000, v69
	v_pk_add_f32 v[64:65], v[64:65], v[66:67]
	v_pk_add_f32 v[66:67], v[38:39], v[36:37]
	v_pk_add_f32 v[68:69], v[34:35], v[26:27]
	s_waitcnt vmcnt(1)
	v_lshlrev_b32_e32 v100, 16, v70
	v_pk_add_f32 v[66:67], v[66:67], v[68:69]
	v_pk_add_f32 v[68:69], v[90:91], v[88:89]
	v_pk_add_f32 v[64:65], v[64:65], v[66:67]
	ds_bpermute_b32 v66, v206, v64
	ds_bpermute_b32 v67, v206, v65
	s_waitcnt lgkmcnt(3)
	v_and_b32_e32 v98, 0xffff0000, v70
	v_lshlrev_b32_e32 v24, 16, v71
	v_and_b32_e32 v70, 0xffff0000, v71
	v_lshlrev_b32_e32 v82, 16, v72
	s_waitcnt lgkmcnt(0)
	v_pk_add_f32 v[64:65], v[64:65], v[66:67]
	ds_bpermute_b32 v66, v207, v64
	ds_bpermute_b32 v67, v207, v65
	v_and_b32_e32 v40, 0xffff0000, v72
	v_lshlrev_b32_e32 v44, 16, v73
	v_and_b32_e32 v54, 0xffff0000, v73
	v_pk_add_f32 v[58:59], v[58:59], v[60:61]
	s_waitcnt lgkmcnt(0)
	v_pk_add_f32 v[64:65], v[64:65], v[66:67]
	ds_bpermute_b32 v66, v208, v64
	ds_bpermute_b32 v67, v208, v65
	s_waitcnt vmcnt(0)
	v_lshlrev_b32_e32 v101, 16, v74
	v_and_b32_e32 v99, 0xffff0000, v74
	v_lshlrev_b32_e32 v25, 16, v75
	v_and_b32_e32 v71, 0xffff0000, v75
	s_waitcnt lgkmcnt(0)
	v_pk_add_f32 v[64:65], v[64:65], v[66:67]
	ds_bpermute_b32 v66, v209, v64
	ds_bpermute_b32 v67, v209, v65
	v_pk_add_f32 v[72:73], v[80:81], v[62:63]
	ds_bpermute_b32 v60, v206, v58
	ds_bpermute_b32 v61, v206, v59
	v_lshlrev_b32_e32 v83, 16, v76
	s_waitcnt lgkmcnt(2)
	v_pk_add_f32 v[64:65], v[64:65], v[66:67]
	v_pk_add_f32 v[66:67], v[94:95], v[92:93]
	v_and_b32_e32 v41, 0xffff0000, v76
	v_pk_add_f32 v[66:67], v[66:67], v[68:69]
	v_pk_add_f32 v[68:69], v[86:87], v[84:85]
	v_lshlrev_b32_e32 v45, 16, v77
	v_and_b32_e32 v55, 0xffff0000, v77
	v_pk_add_f32 v[68:69], v[68:69], v[72:73]
	v_pk_add_f32 v[72:73], v[100:101], v[98:99]
	v_pk_add_f32 v[74:75], v[24:25], v[70:71]
	v_pk_add_f32 v[76:77], v[44:45], v[54:55]
	v_pk_add_f32 v[72:73], v[72:73], v[74:75]
	v_pk_add_f32 v[74:75], v[82:83], v[40:41]
	v_pk_add_f32 v[66:67], v[66:67], v[68:69]
	v_pk_add_f32 v[74:75], v[74:75], v[76:77]
	ds_bpermute_b32 v68, v206, v66
	ds_bpermute_b32 v69, v206, v67
	v_pk_add_f32 v[72:73], v[72:73], v[74:75]
	ds_bpermute_b32 v74, v206, v72
	ds_bpermute_b32 v75, v206, v73
	s_waitcnt lgkmcnt(4)
; __device__ __forceinline__ void gmlp_item(const Params& p, int l, int row0, int hf, unsigned char* lds, int wid0) {
;     ...
;             s[rr] = ((v[rr][0] + v[rr][1]) + (v[rr][2] + v[rr][3])) + ((v[rr][4] + v[rr][5]) + (v[rr][6] + v[rr][7])); }
; #pragma unroll
;         for (int rr = 0; rr < 8; ++rr) s[rr] = wave_sum(s[rr]) * (1.f / 512.f);
; #pragma unroll
;         for (int rr = 0; rr < 8; ++rr) { float q = 0.f;
; #pragma unroll
;             for (int i = 0; i < 8; ++i) { v[rr][i] -= s[rr]; q += v[rr][i] * v[rr][i]; }
;             s[rr] = q; }
; #pragma unroll
;         for (int rr = 0; rr < 8; ++rr) s[rr] = rsqrtf(wave_sum(s[rr]) * (1.f / 512.f) + EPSN);
	v_pk_add_f32 v[58:59], v[58:59], v[60:61]
	ds_bpermute_b32 v60, v207, v58
	ds_bpermute_b32 v61, v207, v59
	s_waitcnt lgkmcnt(4)
	v_pk_add_f32 v[66:67], v[66:67], v[68:69]
	ds_bpermute_b32 v68, v207, v66
	ds_bpermute_b32 v69, v207, v67
	s_waitcnt lgkmcnt(4)
	v_pk_add_f32 v[72:73], v[72:73], v[74:75]
	ds_bpermute_b32 v74, v207, v72
	ds_bpermute_b32 v75, v207, v73
	s_waitcnt lgkmcnt(4)
	v_pk_add_f32 v[58:59], v[58:59], v[60:61]
	ds_bpermute_b32 v60, v208, v58
	ds_bpermute_b32 v61, v208, v59
	s_waitcnt lgkmcnt(4)
	v_pk_add_f32 v[66:67], v[66:67], v[68:69]
	ds_bpermute_b32 v68, v208, v66
	ds_bpermute_b32 v69, v208, v67
	s_waitcnt lgkmcnt(4)
	v_pk_add_f32 v[72:73], v[72:73], v[74:75]
	ds_bpermute_b32 v74, v208, v72
	ds_bpermute_b32 v75, v208, v73
	s_waitcnt lgkmcnt(4)
	v_pk_add_f32 v[58:59], v[58:59], v[60:61]
	ds_bpermute_b32 v60, v209, v58
	ds_bpermute_b32 v61, v209, v59
	s_waitcnt lgkmcnt(4)
	v_pk_add_f32 v[66:67], v[66:67], v[68:69]
	ds_bpermute_b32 v68, v209, v66
	ds_bpermute_b32 v69, v209, v67
	s_waitcnt lgkmcnt(4)
	v_pk_add_f32 v[72:73], v[72:73], v[74:75]
	ds_bpermute_b32 v74, v209, v72
	ds_bpermute_b32 v75, v209, v73
	s_waitcnt lgkmcnt(4)
	v_pk_add_f32 v[58:59], v[58:59], v[60:61]
	ds_bpermute_b32 v76, v229, v64
	ds_bpermute_b32 v77, v229, v65
	ds_bpermute_b32 v60, v229, v58
	ds_bpermute_b32 v61, v229, v59
	s_waitcnt lgkmcnt(6)
	v_pk_add_f32 v[66:67], v[66:67], v[68:69]
	ds_bpermute_b32 v68, v229, v66
	ds_bpermute_b32 v69, v229, v67
	s_waitcnt lgkmcnt(6)
	v_pk_add_f32 v[72:73], v[72:73], v[74:75]
	s_waitcnt lgkmcnt(4)
	v_pk_add_f32 v[64:65], v[64:65], v[76:77]
	ds_bpermute_b32 v74, v229, v72
	ds_bpermute_b32 v75, v229, v73
	s_waitcnt lgkmcnt(4)
	v_pk_add_f32 v[58:59], v[58:59], v[60:61]
	ds_bpermute_b32 v76, v230, v64
	ds_bpermute_b32 v77, v230, v65
	ds_bpermute_b32 v60, v230, v58
	ds_bpermute_b32 v61, v230, v59
	s_waitcnt lgkmcnt(6)
	v_pk_add_f32 v[66:67], v[66:67], v[68:69]
	ds_bpermute_b32 v68, v230, v66
	ds_bpermute_b32 v69, v230, v67
	s_waitcnt lgkmcnt(6)
	v_pk_add_f32 v[72:73], v[72:73], v[74:75]
	ds_bpermute_b32 v74, v230, v72
	ds_bpermute_b32 v75, v230, v73
	s_waitcnt lgkmcnt(6)
	v_pk_add_f32 v[106:107], v[64:65], v[76:77]
	s_waitcnt lgkmcnt(4)
	v_pk_add_f32 v[104:105], v[58:59], v[60:61]
	v_pk_fma_f32 v[58:59], v[106:107], s[30:31], v[52:53] op_sel_hi:[1,0,1] neg_lo:[1,0,0] neg_hi:[1,0,0]
	v_pk_fma_f32 v[64:65], v[104:105], s[30:31], v[18:19] op_sel_hi:[1,0,1] neg_lo:[1,0,0] neg_hi:[1,0,0]
	v_pk_fma_f32 v[60:61], v[106:107], s[30:31], v[56:57] op_sel_hi:[1,0,1] neg_lo:[1,0,0] neg_hi:[1,0,0]
	v_pk_mul_f32 v[18:19], v[58:59], v[58:59]
	v_pk_fma_f32 v[76:77], v[104:105], s[30:31], v[42:43] op_sel_hi:[1,0,1] neg_lo:[1,0,0] neg_hi:[1,0,0]
	v_pk_fma_f32 v[18:19], v[60:61], v[60:61], v[18:19]
	v_pk_fma_f32 v[56:57], v[106:107], s[30:31], v[50:51] op_sel_hi:[1,0,1] neg_lo:[1,0,0] neg_hi:[1,0,0]
	s_waitcnt lgkmcnt(2)
	v_pk_add_f32 v[108:109], v[66:67], v[68:69]
	v_pk_fma_f32 v[78:79], v[104:105], s[30:31], v[46:47] op_sel_hi:[1,0,1] neg_lo:[1,0,0] neg_hi:[1,0,0]
	v_pk_mul_f32 v[42:43], v[76:77], v[76:77]
	v_pk_fma_f32 v[18:19], v[56:57], v[56:57], v[18:19]
	v_pk_fma_f32 v[52:53], v[106:107], s[30:31], v[48:49] op_sel_hi:[1,0,1] neg_lo:[1,0,0] neg_hi:[1,0,0]
	s_waitcnt lgkmcnt(0)
	v_pk_add_f32 v[110:111], v[72:73], v[74:75]
	v_pk_fma_f32 v[42:43], v[78:79], v[78:79], v[42:43]
	v_pk_fma_f32 v[74:75], v[104:105], s[30:31], v[32:33] op_sel_hi:[1,0,1] neg_lo:[1,0,0] neg_hi:[1,0,0]
	v_pk_fma_f32 v[18:19], v[52:53], v[52:53], v[18:19]
	v_pk_fma_f32 v[50:51], v[106:107], s[30:31], v[38:39] op_sel_hi:[1,0,1] neg_lo:[1,0,0] neg_hi:[1,0,0]
	v_pk_fma_f32 v[38:39], v[108:109], s[30:31], v[92:93] op_sel_hi:[1,0,1] neg_lo:[1,0,0] neg_hi:[1,0,0]
	v_pk_fma_f32 v[32:33], v[74:75], v[74:75], v[42:43]
	v_pk_fma_f32 v[114:115], v[50:51], v[50:51], v[18:19]
	v_pk_fma_f32 v[42:43], v[108:109], s[30:31], v[94:95] op_sel_hi:[1,0,1] neg_lo:[1,0,0] neg_hi:[1,0,0]
	v_pk_mul_f32 v[18:19], v[38:39], v[38:39]
	v_pk_fma_f32 v[48:49], v[106:107], s[30:31], v[36:37] op_sel_hi:[1,0,1] neg_lo:[1,0,0] neg_hi:[1,0,0]
	v_pk_fma_f32 v[18:19], v[42:43], v[42:43], v[18:19]
	v_pk_fma_f32 v[36:37], v[108:109], s[30:31], v[90:91] op_sel_hi:[1,0,1] neg_lo:[1,0,0] neg_hi:[1,0,0]
	v_pk_fma_f32 v[72:73], v[104:105], s[30:31], v[30:31] op_sel_hi:[1,0,1] neg_lo:[1,0,0] neg_hi:[1,0,0]
	v_pk_fma_f32 v[46:47], v[106:107], s[30:31], v[34:35] op_sel_hi:[1,0,1] neg_lo:[1,0,0] neg_hi:[1,0,0]
	v_pk_fma_f32 v[18:19], v[36:37], v[36:37], v[18:19]
	v_pk_fma_f32 v[34:35], v[108:109], s[30:31], v[88:89] op_sel_hi:[1,0,1] neg_lo:[1,0,0] neg_hi:[1,0,0]
	v_pk_fma_f32 v[30:31], v[72:73], v[72:73], v[32:33]
	v_pk_fma_f32 v[18:19], v[34:35], v[34:35], v[18:19]
	v_pk_fma_f32 v[32:33], v[108:109], s[30:31], v[86:87] op_sel_hi:[1,0,1] neg_lo:[1,0,0] neg_hi:[1,0,0]
	v_pk_fma_f32 v[68:69], v[104:105], s[30:31], v[28:29] op_sel_hi:[1,0,1] neg_lo:[1,0,0] neg_hi:[1,0,0]
	v_pk_fma_f32 v[86:87], v[32:33], v[32:33], v[18:19]
	v_pk_fma_f32 v[18:19], v[110:111], s[30:31], v[98:99] op_sel_hi:[1,0,1] neg_lo:[1,0,0] neg_hi:[1,0,0]
	v_pk_fma_f32 v[112:113], v[68:69], v[68:69], v[30:31]
	v_pk_fma_f32 v[66:67], v[104:105], s[30:31], v[20:21] op_sel_hi:[1,0,1] neg_lo:[1,0,0] neg_hi:[1,0,0]
	v_pk_fma_f32 v[28:29], v[108:109], s[30:31], v[80:81] op_sel_hi:[1,0,1] neg_lo:[1,0,0] neg_hi:[1,0,0]
	v_pk_fma_f32 v[20:21], v[110:111], s[30:31], v[100:101] op_sel_hi:[1,0,1] neg_lo:[1,0,0] neg_hi:[1,0,0]
	v_pk_mul_f32 v[80:81], v[18:19], v[18:19]
	v_pk_fma_f32 v[30:31], v[108:109], s[30:31], v[84:85] op_sel_hi:[1,0,1] neg_lo:[1,0,0] neg_hi:[1,0,0]
	v_pk_fma_f32 v[84:85], v[20:21], v[20:21], v[80:81]
	v_pk_fma_f32 v[80:81], v[66:67], v[66:67], v[112:113]
	v_pk_fma_f32 v[24:25], v[110:111], s[30:31], v[24:25] op_sel_hi:[1,0,1] neg_lo:[1,0,0] neg_hi:[1,0,0]
	v_pk_fma_f32 v[88:89], v[64:65], v[64:65], v[80:81]
	v_pk_fma_f32 v[80:81], v[104:105], s[30:31], v[22:23] op_sel_hi:[1,0,1] neg_lo:[1,0,0] neg_hi:[1,0,0]
	v_pk_fma_f32 v[22:23], v[110:111], s[30:31], v[70:71] op_sel_hi:[1,0,1] neg_lo:[1,0,0] neg_hi:[1,0,0]
	v_pk_fma_f32 v[88:89], v[80:81], v[80:81], v[88:89]
	ds_bpermute_b32 v90, v206, v88
	ds_bpermute_b32 v91, v206, v89
	v_pk_fma_f32 v[70:71], v[48:49], v[48:49], v[114:115]
	v_pk_fma_f32 v[84:85], v[24:25], v[24:25], v[84:85]
	v_pk_fma_f32 v[92:93], v[46:47], v[46:47], v[70:71]
	v_pk_fma_f32 v[70:71], v[106:107], s[30:31], v[26:27] op_sel_hi:[1,0,1] neg_lo:[1,0,0] neg_hi:[1,0,0]
	s_waitcnt lgkmcnt(0)
; __device__ __forceinline__ bf16 f2bf(float v) { return (bf16)(pg8::cvt_pk_bf16(v, 0.f) & 0xffffu); }
; __device__ __forceinline__ void gmlp_item(const Params& p, int l, int row0, int hf, unsigned char* lds, int wid0) {
;     ...
;         for (int rr = 0; rr < 8; ++rr) s[rr] = wave_sum(s[rr]) * (1.f / 512.f);
; #pragma unroll
;         for (int rr = 0; rr < 8; ++rr) { float q = 0.f;
; #pragma unroll
;             for (int i = 0; i < 8; ++i) { v[rr][i] -= s[rr]; q += v[rr][i] * v[rr][i]; }
;             s[rr] = q; }
; #pragma unroll
;         for (int rr = 0; rr < 8; ++rr) s[rr] = rsqrtf(wave_sum(s[rr]) * (1.f / 512.f) + EPSN);
;         if ((lane >> 5) == hf) {
; #pragma unroll
;             for (int rr = 0; rr < 8; ++rr) { const int q = wid * 16 + hb * 8 + rr;
; #pragma unroll
;                 for (int i = 0; i < 8; ++i) vT[(8 * (lane & 31) + i) * 136 + q] = f2bf(v[rr][i] * s[rr] * g8[i] + b8[i]); } }
	v_pk_add_f32 v[88:89], v[88:89], v[90:91]
	v_pk_fma_f32 v[92:93], v[70:71], v[70:71], v[92:93]
	ds_bpermute_b32 v90, v207, v88
	ds_bpermute_b32 v91, v207, v89
	ds_bpermute_b32 v94, v206, v92
	ds_bpermute_b32 v95, v206, v93
	v_pk_fma_f32 v[26:27], v[110:111], s[30:31], v[82:83] op_sel_hi:[1,0,1] neg_lo:[1,0,0] neg_hi:[1,0,0]
	v_pk_fma_f32 v[84:85], v[22:23], v[22:23], v[84:85]
	s_waitcnt lgkmcnt(2)
	v_pk_add_f32 v[82:83], v[88:89], v[90:91]
	ds_bpermute_b32 v88, v208, v82
	s_waitcnt lgkmcnt(1)
	v_pk_add_f32 v[90:91], v[92:93], v[94:95]
	ds_bpermute_b32 v89, v208, v83
	ds_bpermute_b32 v92, v207, v90
	ds_bpermute_b32 v93, v207, v91
	v_pk_fma_f32 v[94:95], v[26:27], v[26:27], v[84:85]
	v_pk_fma_f32 v[40:41], v[110:111], s[30:31], v[40:41] op_sel_hi:[1,0,1] neg_lo:[1,0,0] neg_hi:[1,0,0]
	s_waitcnt lgkmcnt(2)
	v_pk_add_f32 v[82:83], v[82:83], v[88:89]
	v_pk_fma_f32 v[44:45], v[110:111], s[30:31], v[44:45] op_sel_hi:[1,0,1] neg_lo:[1,0,0] neg_hi:[1,0,0]
	s_waitcnt lgkmcnt(0)
	v_pk_add_f32 v[88:89], v[90:91], v[92:93]
	ds_bpermute_b32 v90, v208, v88
	ds_bpermute_b32 v91, v208, v89
	v_pk_fma_f32 v[86:87], v[30:31], v[30:31], v[86:87]
	v_pk_fma_f32 v[92:93], v[40:41], v[40:41], v[94:95]
	v_pk_fma_f32 v[86:87], v[28:29], v[28:29], v[86:87]
	v_pk_fma_f32 v[62:63], v[108:109], s[30:31], v[62:63] op_sel_hi:[1,0,1] neg_lo:[1,0,0] neg_hi:[1,0,0]
	s_waitcnt lgkmcnt(0)
	v_pk_add_f32 v[88:89], v[88:89], v[90:91]
	ds_bpermute_b32 v90, v209, v88
	ds_bpermute_b32 v91, v209, v89
	v_pk_fma_f32 v[92:93], v[44:45], v[44:45], v[92:93]
	v_pk_fma_f32 v[54:55], v[110:111], s[30:31], v[54:55] op_sel_hi:[1,0,1] neg_lo:[1,0,0] neg_hi:[1,0,0]
	v_pk_fma_f32 v[86:87], v[62:63], v[62:63], v[86:87]
	v_pk_fma_f32 v[92:93], v[54:55], v[54:55], v[92:93]
	s_waitcnt lgkmcnt(0)
	v_pk_add_f32 v[88:89], v[88:89], v[90:91]
	ds_bpermute_b32 v90, v206, v86
	ds_bpermute_b32 v91, v206, v87
	ds_bpermute_b32 v94, v206, v92
	ds_bpermute_b32 v95, v206, v93
	ds_bpermute_b32 v98, v229, v88
	ds_bpermute_b32 v99, v229, v89
	s_waitcnt lgkmcnt(4)
	v_pk_add_f32 v[86:87], v[86:87], v[90:91]
	ds_bpermute_b32 v90, v207, v86
	s_waitcnt lgkmcnt(3)
	v_pk_add_f32 v[92:93], v[92:93], v[94:95]
	ds_bpermute_b32 v91, v207, v87
	ds_bpermute_b32 v94, v207, v92
	ds_bpermute_b32 v95, v207, v93
	ds_bpermute_b32 v84, v209, v82
	ds_bpermute_b32 v85, v209, v83
	s_waitcnt lgkmcnt(4)
	v_pk_add_f32 v[90:91], v[86:87], v[90:91]
	ds_bpermute_b32 v100, v208, v90
	s_waitcnt lgkmcnt(3)
	v_pk_add_f32 v[92:93], v[92:93], v[94:95]
	ds_bpermute_b32 v101, v208, v91
	ds_bpermute_b32 v94, v208, v92
	ds_bpermute_b32 v95, v208, v93
	v_pk_add_f32 v[86:87], v[88:89], v[98:99]
	s_waitcnt lgkmcnt(4)
	v_pk_add_f32 v[82:83], v[82:83], v[84:85]
	s_waitcnt lgkmcnt(2)
	v_pk_add_f32 v[90:91], v[90:91], v[100:101]
	ds_bpermute_b32 v98, v209, v90
	s_waitcnt lgkmcnt(1)
	v_pk_add_f32 v[92:93], v[92:93], v[94:95]
	ds_bpermute_b32 v99, v209, v91
	ds_bpermute_b32 v94, v209, v92
	ds_bpermute_b32 v95, v209, v93
	ds_bpermute_b32 v84, v229, v82
	ds_bpermute_b32 v85, v229, v83
	s_waitcnt lgkmcnt(4)
	v_pk_add_f32 v[90:91], v[90:91], v[98:99]
	ds_bpermute_b32 v98, v229, v90
	s_waitcnt lgkmcnt(3)
	v_pk_add_f32 v[94:95], v[92:93], v[94:95]
	ds_bpermute_b32 v99, v229, v91
	ds_bpermute_b32 v100, v229, v94
	ds_bpermute_b32 v101, v229, v95
	s_waitcnt lgkmcnt(4)
	v_pk_add_f32 v[82:83], v[82:83], v[84:85]
	ds_bpermute_b32 v84, v230, v82
	s_waitcnt lgkmcnt(3)
	v_pk_add_f32 v[90:91], v[90:91], v[98:99]
	ds_bpermute_b32 v85, v230, v83
	s_waitcnt lgkmcnt(2)
	v_pk_add_f32 v[94:95], v[94:95], v[100:101]
	ds_bpermute_b32 v88, v230, v86
	ds_bpermute_b32 v89, v230, v87
	ds_bpermute_b32 v92, v230, v90
	ds_bpermute_b32 v93, v230, v91
	ds_bpermute_b32 v98, v230, v94
	ds_bpermute_b32 v99, v230, v95
	s_and_saveexec_b64 s[42:43], s[38:39]
	s_cbranch_execz .LBB0_212
	s_mov_b32 s0, 0x358637bd
	s_waitcnt lgkmcnt(0)
	v_pk_add_f32 v[94:95], v[94:95], v[98:99]
	v_mov_b64_e32 v[98:99], s[0:1]
	v_pk_fma_f32 v[94:95], v[94:95], s[30:31], v[98:99] op_sel_hi:[1,0,0]
	v_pk_add_f32 v[90:91], v[90:91], v[92:93]
	v_mul_f32_e32 v100, 0x4b800000, v95
	v_cmp_gt_f32_e64 s[0:1], s87, v95
	v_pk_fma_f32 v[90:91], v[90:91], s[30:31], v[98:99] op_sel_hi:[1,0,0]
	v_cmp_gt_f32_e32 vcc, s87, v94
	v_cndmask_b32_e64 v95, v95, v100, s[0:1]
	v_rsq_f32_e32 v95, v95
	s_nop 0
	v_mul_f32_e32 v92, 0x4b800000, v91
	v_pk_add_f32 v[86:87], v[86:87], v[88:89]
	v_pk_add_f32 v[82:83], v[82:83], v[84:85]
	v_mul_f32_e32 v100, 0x45800000, v95
	v_cndmask_b32_e64 v95, v95, v100, s[0:1]
	v_mul_f32_e32 v100, 0x4b800000, v94
	v_cmp_gt_f32_e64 s[0:1], s87, v91
	v_cndmask_b32_e32 v94, v94, v100, vcc
	v_rsq_f32_e32 v94, v94
	s_nop 0
	v_cndmask_b32_e64 v91, v91, v92, s[0:1]
	v_rsq_f32_e32 v91, v91
	s_nop 0
	v_pk_fma_f32 v[86:87], v[86:87], s[30:31], v[98:99] op_sel_hi:[1,0,0]
	v_mul_f32_e32 v100, 0x45800000, v94
	v_cndmask_b32_e32 v94, v94, v100, vcc
	v_mul_f32_e32 v92, 0x45800000, v91
	v_cmp_gt_f32_e32 vcc, s87, v90
	v_cndmask_b32_e64 v91, v91, v92, s[0:1]
	v_mul_f32_e32 v92, 0x4b800000, v90
	v_mul_f32_e32 v88, 0x4b800000, v87
	v_cmp_gt_f32_e64 s[0:1], s87, v87
	v_cndmask_b32_e32 v90, v90, v92, vcc
	v_rsq_f32_e32 v90, v90
	s_nop 0
	v_cndmask_b32_e64 v87, v87, v88, s[0:1]
	v_rsq_f32_e32 v87, v87
	s_nop 0
	v_pk_fma_f32 v[82:83], v[82:83], s[30:31], v[98:99] op_sel_hi:[1,0,0]
	v_mul_f32_e32 v92, 0x45800000, v90
	v_cndmask_b32_e32 v90, v90, v92, vcc
	v_mul_f32_e32 v88, 0x45800000, v87
	v_cmp_gt_f32_e32 vcc, s87, v86
	v_cndmask_b32_e64 v87, v87, v88, s[0:1]
	v_mul_f32_e32 v88, 0x4b800000, v86
	v_mul_f32_e32 v84, 0x4b800000, v83
	v_cmp_gt_f32_e64 s[0:1], s87, v83
	v_cndmask_b32_e32 v86, v86, v88, vcc
; __device__ __forceinline__ bf16 f2bf(float v) { return (bf16)(pg8::cvt_pk_bf16(v, 0.f) & 0xffffu); }
; __device__ __forceinline__ void gmlp_item(const Params& p, int l, int row0, int hf, unsigned char* lds, int wid0) {
;     ...
;         if ((lane >> 5) == hf) {
; #pragma unroll
;             for (int rr = 0; rr < 8; ++rr) { const int q = wid * 16 + hb * 8 + rr;
; #pragma unroll
;                 for (int i = 0; i < 8; ++i) vT[(8 * (lane & 31) + i) * 136 + q] = f2bf(v[rr][i] * s[rr] * g8[i] + b8[i]); } }
	v_rsq_f32_e32 v86, v86
	s_nop 0
	v_cndmask_b32_e64 v83, v83, v84, s[0:1]
	v_rsq_f32_e32 v83, v83
	s_nop 0
	v_mul_f32_e32 v88, 0x45800000, v86
	v_cndmask_b32_e32 v86, v86, v88, vcc
	v_mul_f32_e32 v84, 0x45800000, v83
	v_cmp_gt_f32_e32 vcc, s87, v82
	v_cndmask_b32_e64 v83, v83, v84, s[0:1]
	v_mul_f32_e32 v84, 0x4b800000, v82
	v_cndmask_b32_e32 v82, v82, v84, vcc
	v_rsq_f32_e32 v82, v82
	s_nop 0
	v_mul_f32_e32 v84, 0x45800000, v82
	v_cndmask_b32_e32 v82, v82, v84, vcc
	v_lshl_add_u32 v84, s46, 4, v103
	v_mul_f32_e32 v78, v78, v82
	v_mul_f32_e32 v79, v79, v83
	v_mul_f32_e32 v60, v60, v86
	v_mul_f32_e32 v61, v61, v87
	v_mul_f32_e32 v42, v42, v90
	v_mul_f32_e32 v43, v43, v91
	v_mul_f32_e32 v20, v20, v94
	v_mul_f32_e32 v21, v21, v95
	v_fma_f32 v78, v0, v78, v8
	v_fma_f32 v79, v0, v79, v8
	v_fma_f32 v60, v0, v60, v8
	v_fma_f32 v61, v0, v61, v8
	v_fma_f32 v42, v0, v42, v8
	v_fma_f32 v43, v0, v43, v8
	v_fma_f32 v20, v0, v20, v8
	v_fma_f32 v21, v0, v21, v8
	v_cvt_pk_bf16_f32 v98, v78, v79
	v_cvt_pk_bf16_f32 v99, v60, v61
	v_cvt_pk_bf16_f32 v100, v42, v43
	v_cvt_pk_bf16_f32 v101, v20, v21
	ds_write_b128 v84, v[98:101]
	v_mul_f32_e32 v76, v76, v82
	v_mul_f32_e32 v77, v77, v83
	v_mul_f32_e32 v58, v58, v86
	v_mul_f32_e32 v59, v59, v87
	v_mul_f32_e32 v38, v38, v90
	v_mul_f32_e32 v39, v39, v91
	v_mul_f32_e32 v18, v18, v94
	v_mul_f32_e32 v19, v19, v95
	v_fma_f32 v76, v1, v76, v9
	v_fma_f32 v77, v1, v77, v9
	v_fma_f32 v58, v1, v58, v9
	v_fma_f32 v59, v1, v59, v9
	v_fma_f32 v38, v1, v38, v9
	v_fma_f32 v39, v1, v39, v9
	v_fma_f32 v18, v1, v18, v9
	v_fma_f32 v19, v1, v19, v9
	v_cvt_pk_bf16_f32 v98, v76, v77
	v_cvt_pk_bf16_f32 v99, v58, v59
	v_cvt_pk_bf16_f32 v100, v38, v39
	v_cvt_pk_bf16_f32 v101, v18, v19
	ds_write_b128 v84, v[98:101] offset:272
	v_mul_f32_e32 v74, v74, v82
	v_mul_f32_e32 v75, v75, v83
	v_mul_f32_e32 v56, v56, v86
	v_mul_f32_e32 v57, v57, v87
	v_mul_f32_e32 v36, v36, v90
	v_mul_f32_e32 v37, v37, v91
	v_mul_f32_e32 v24, v24, v94
	v_mul_f32_e32 v25, v25, v95
	v_fma_f32 v74, v2, v74, v10
	v_fma_f32 v75, v2, v75, v10
	v_fma_f32 v56, v2, v56, v10
	v_fma_f32 v57, v2, v57, v10
	v_fma_f32 v36, v2, v36, v10
	v_fma_f32 v37, v2, v37, v10
	v_fma_f32 v24, v2, v24, v10
	v_fma_f32 v25, v2, v25, v10
	v_cvt_pk_bf16_f32 v98, v74, v75
	v_cvt_pk_bf16_f32 v99, v56, v57
	v_cvt_pk_bf16_f32 v100, v36, v37
	v_cvt_pk_bf16_f32 v101, v24, v25
	ds_write_b128 v84, v[98:101] offset:544
	v_mul_f32_e32 v72, v72, v82
	v_mul_f32_e32 v73, v73, v83
	v_mul_f32_e32 v52, v52, v86
	v_mul_f32_e32 v53, v53, v87
	v_mul_f32_e32 v34, v34, v90
	v_mul_f32_e32 v35, v35, v91
	v_mul_f32_e32 v22, v22, v94
	v_mul_f32_e32 v23, v23, v95
	v_fma_f32 v72, v3, v72, v11
	v_fma_f32 v73, v3, v73, v11
	v_fma_f32 v52, v3, v52, v11
	v_fma_f32 v53, v3, v53, v11
	v_fma_f32 v34, v3, v34, v11
	v_fma_f32 v35, v3, v35, v11
	v_fma_f32 v22, v3, v22, v11
	v_fma_f32 v23, v3, v23, v11
	v_cvt_pk_bf16_f32 v98, v72, v73
	v_cvt_pk_bf16_f32 v99, v52, v53
	v_cvt_pk_bf16_f32 v100, v34, v35
	v_cvt_pk_bf16_f32 v101, v22, v23
	ds_write_b128 v84, v[98:101] offset:816
	v_mul_f32_e32 v68, v68, v82
	v_mul_f32_e32 v69, v69, v83
	v_mul_f32_e32 v50, v50, v86
	v_mul_f32_e32 v51, v51, v87
	v_mul_f32_e32 v32, v32, v90
	v_mul_f32_e32 v33, v33, v91
	v_mul_f32_e32 v26, v26, v94
	v_mul_f32_e32 v27, v27, v95
	v_fma_f32 v68, v4, v68, v12
	v_fma_f32 v69, v4, v69, v12
	v_fma_f32 v50, v4, v50, v12
	v_fma_f32 v51, v4, v51, v12
	v_fma_f32 v32, v4, v32, v12
	v_fma_f32 v33, v4, v33, v12
	v_fma_f32 v26, v4, v26, v12
	v_fma_f32 v27, v4, v27, v12
	v_cvt_pk_bf16_f32 v98, v68, v69
	v_cvt_pk_bf16_f32 v99, v50, v51
	v_cvt_pk_bf16_f32 v100, v32, v33
	v_cvt_pk_bf16_f32 v101, v26, v27
	ds_write_b128 v84, v[98:101] offset:1088
	v_mul_f32_e32 v66, v66, v82
	v_mul_f32_e32 v67, v67, v83
	v_mul_f32_e32 v48, v48, v86
	v_mul_f32_e32 v49, v49, v87
	v_mul_f32_e32 v30, v30, v90
	v_mul_f32_e32 v31, v31, v91
	v_mul_f32_e32 v40, v40, v94
	v_mul_f32_e32 v41, v41, v95
	v_fma_f32 v66, v5, v66, v13
	v_fma_f32 v67, v5, v67, v13
	v_fma_f32 v48, v5, v48, v13
	v_fma_f32 v49, v5, v49, v13
	v_fma_f32 v30, v5, v30, v13
	v_fma_f32 v31, v5, v31, v13
	v_fma_f32 v40, v5, v40, v13
	v_fma_f32 v41, v5, v41, v13
	v_cvt_pk_bf16_f32 v98, v66, v67
	v_cvt_pk_bf16_f32 v99, v48, v49
	v_cvt_pk_bf16_f32 v100, v30, v31
	v_cvt_pk_bf16_f32 v101, v40, v41
	ds_write_b128 v84, v[98:101] offset:1360
	v_mul_f32_e32 v64, v64, v82
	v_mul_f32_e32 v65, v65, v83
	v_mul_f32_e32 v46, v46, v86
	v_mul_f32_e32 v47, v47, v87
	v_mul_f32_e32 v28, v28, v90
	v_mul_f32_e32 v29, v29, v91
	v_mul_f32_e32 v44, v44, v94
	v_mul_f32_e32 v45, v45, v95
	v_fma_f32 v64, v6, v64, v14
	v_fma_f32 v65, v6, v65, v14
	v_fma_f32 v46, v6, v46, v14
	v_fma_f32 v47, v6, v47, v14
	v_fma_f32 v28, v6, v28, v14
	v_fma_f32 v29, v6, v29, v14
	v_fma_f32 v44, v6, v44, v14
	v_fma_f32 v45, v6, v45, v14
	v_cvt_pk_bf16_f32 v98, v64, v65
	v_cvt_pk_bf16_f32 v99, v46, v47
	v_cvt_pk_bf16_f32 v100, v28, v29
	v_cvt_pk_bf16_f32 v101, v44, v45
	ds_write_b128 v84, v[98:101] offset:1632
	v_mul_f32_e32 v80, v80, v82
	v_mul_f32_e32 v81, v81, v83
	v_mul_f32_e32 v70, v70, v86
	v_mul_f32_e32 v71, v71, v87
	v_mul_f32_e32 v62, v62, v90
	v_mul_f32_e32 v63, v63, v91
	v_mul_f32_e32 v54, v54, v94
	v_mul_f32_e32 v55, v55, v95
	v_fma_f32 v80, v7, v80, v15
	v_fma_f32 v81, v7, v81, v15
	v_fma_f32 v70, v7, v70, v15
	v_fma_f32 v71, v7, v71, v15
	v_fma_f32 v62, v7, v62, v15
	v_fma_f32 v63, v7, v63, v15
	v_fma_f32 v54, v7, v54, v15
	v_fma_f32 v55, v7, v55, v15
	v_cvt_pk_bf16_f32 v98, v80, v81
	v_cvt_pk_bf16_f32 v99, v70, v71
	v_cvt_pk_bf16_f32 v100, v62, v63
	v_cvt_pk_bf16_f32 v101, v54, v55
	ds_write_b128 v84, v[98:101] offset:1904
	s_branch .LBB0_212

; __device__ __forceinline__ float bf2f(unsigned b) { return __uint_as_float(b << 16); }
; __device__ __forceinline__ void ld10(const bf16* row, int t0, float (&o)[10]) {
;     const u32x4 raw = *(const u32x4*)(row + t0);
;     o[0] = t0 > 0 ? bf2f(row[t0 - 1]) : 0.f; o[9] = t0 + 8 < SEQ ? bf2f(row[t0 + 8]) : 0.f;
;     o[1] = bf2f(raw.x & 0xffffu); o[2] = bf2f(raw.x >> 16); o[3] = bf2f(raw.y & 0xffffu); o[4] = bf2f(raw.y >> 16); o[5] = bf2f(raw.z & 0xffffu); o[6] = bf2f(raw.z >> 16); o[7] = bf2f(raw.w & 0xffffu); o[8] = bf2f(raw.w >> 16);
; }
; __device__ __forceinline__ void hyena_channel(const Params& p, int l, int c, unsigned char* lds, int wid0) {
;     ...
;             for (int j = 0; j < 2; ++j) { const int t0 = 8 * tid + 4096 * j; float u[2][8];
; #pragma unroll
;                 for (int b = 0; b < 2; ++b) { const bf16* zb = zT + (size_t)(b * 1536 + c) * SEQ; float r1[10], r2[10]; ld10(zb + (size_t)512 * SEQ, t0, r1); ld10(zb + (size_t)1024 * SEQ, t0, r2);
; #pragma unroll
;                     for (int i = 0; i < 8; ++i) u[b][i] = (w10 * r1[i] + w11 * r1[i + 1] + w12 * r1[i + 2] + b1) * (w20 * r2[i] + w21 * r2[i + 1] + w22 * r2[i + 2] + b2); }
.LBB0_234:
	v_add_u32_e32 v16, s0, v238
	v_ashrrev_i32_e32 v17, 31, v16
	v_cmp_lt_i32_e32 vcc, 0, v16
	v_mov_b32_e32 v96, v16
	v_lshl_add_u64 v[28:29], v[16:17], 1, s[58:59]
	v_lshl_add_u64 v[30:31], v[16:17], 1, s[54:55]
	v_lshl_add_u64 v[32:33], v[16:17], 1, s[44:45]
	v_lshl_add_u64 v[22:23], v[16:17], 1, s[82:83]
	global_load_dwordx4 v[4:7], v[28:29], off
	global_load_dwordx4 v[8:11], v[30:31], off
	global_load_dwordx4 v[12:15], v[32:33], off
	global_load_dwordx4 v[0:3], v[22:23], off
	v_mov_b32_e32 v26, 0
	v_mov_b32_e32 v27, 0
	v_mov_b32_e32 v20, 0
	v_mov_b32_e32 v21, 0
	v_mov_b32_e32 v24, 0
	v_mov_b32_e32 v25, 0
	v_mov_b32_e32 v18, 0
	v_mov_b32_e32 v19, 0
	v_cmp_gt_i32_e64 s[0:1], s50, v16
	s_and_saveexec_b64 s[48:49], vcc
	s_cbranch_execz .Lhy_ld_a
	global_load_ushort v26, v[28:29], off offset:-2
	global_load_ushort v27, v[30:31], off offset:-2
	global_load_ushort v20, v[32:33], off offset:-2
	global_load_ushort v21, v[22:23], off offset:-2
.Lhy_ld_a:
	s_or_b64 exec, exec, s[48:49]
	s_and_saveexec_b64 s[48:49], s[0:1]
	s_cbranch_execz .Lhy_ld_b
	global_load_ushort v24, v[28:29], off offset:16
	global_load_ushort v25, v[30:31], off offset:16
	global_load_ushort v18, v[32:33], off offset:16
	global_load_ushort v19, v[22:23], off offset:16
.Lhy_ld_b:
	s_or_b64 exec, exec, s[48:49]
	s_waitcnt vmcnt(0)
	v_lshlrev_b32_e32 v26, 16, v26
	v_lshlrev_b32_e32 v27, 16, v27
	v_lshlrev_b32_e32 v20, 16, v20
	v_lshlrev_b32_e32 v21, 16, v21
	v_lshlrev_b32_e32 v24, 16, v24
	v_lshlrev_b32_e32 v25, 16, v25
	v_lshlrev_b32_e32 v18, 16, v18
	v_lshlrev_b32_e32 v19, 16, v19
	s_branch .LBB0_233
